# in-proj 13th-tile units run an out-of-line copy of the mainloop with the cluster skips; the main in-proj loops carry no per-cluster test
# speedup vs baseline: 1.0116x; 1.0060x over previous
; DEVI size_t gemm_offB(const Gemm& g, const Unit& u) { return (g.split ? (size_t)(u.b >> 2) * g.sB + (size_t)(u.b & 3) * g.sB_lo : (size_t)u.b * g.sB) + (size_t)(u.pm >> g.pmsh) * g.sBpm; }
; #define PG8_STAGE(bufoff, gbase, voff) do { _Pragma("unroll") for (int _i = 0; _i < 2; ++_i) \
;         __builtin_amdgcn_global_load_lds((const unsigned*)((const char*)(gbase) + (voff)[_i]), (LAS unsigned*)(lds + (bufoff) + ldsw + _i * 8192), 16, 0, 0); } while (0)
; #define PG8_LDA(dst, b, h) do { _Pragma("unroll") for (int m = 0; m < 4; ++m) _Pragma("unroll") for (int k = 0; k < 2; ++k) dst[m][k] = *(const LAS bf16x8*)(lds + PG8_SA(b, h) + aoff + m * 2048 + k * 1024); } while (0)
; #define PG8_LDB(dst, b, h) do { _Pragma("unroll") for (int n = 0; n < 2; ++n) _Pragma("unroll") for (int k = 0; k < 2; ++k) dst[n][k] = *(const LAS bf16x8*)(lds + PG8_SB(b, h) + boff + n * 2048 + k * 1024); } while (0)
; #define PG8_WAIT_L(n) asm volatile("s_waitcnt lgkmcnt(" #n ")" ::: "memory")
; #define PG8_BAR __builtin_amdgcn_s_barrier()
; #define PG8_SCHED __builtin_amdgcn_sched_barrier(0)
; template <class Epi>
; DEVI void gemm_phase(LAS unsigned char* lds, const Gemm g, const Epi& E) {
;     ...
;         const bool has_next = unit_next(g, ui + 1, nxt);
;         const char* nA = has_next ? (const char*)g.A + gemm_offA(g, nxt) * 2 + (size_t)nxt.pm * tstepA : cA;
;         const char* nB = has_next ? (const char*)g.Bt + gemm_offB(g, nxt) * 2 + (size_t)nxt.pn * tstepB : cB;
;         for (int t = 0; t < nt; t += 2) {
;             const bool last = (t == nt - 2);
;             const char* a1 = cA + (size_t)(t + 1) * kstep;
;             const char* a2 = last ? nA : cA + (size_t)(t + 2) * kstep; const char* b2 = last ? nB : cB + (size_t)(t + 2) * kstep;
;             const char* a3 = a2 + kstep; const char* b3 = b2 + kstep;
;             PG8_LDB(B0, 0, 0); PG8_SCHED; PG8_LDA(At, 0, 0); PG8_STAGE(PG8_SA(1, 1), a1 + hstepA, voffA);
;             PG8_WAIT_L(8); PG8_BAR; PG8_WAIT_L(0); PG8_MMA(0, 0, At, B0); PG8_BAR; PG8_SCHED;
;             PG8_LDB(B1, 0, 1); PG8_STAGE(PG8_SB(0, 0), b2, voffB);
;             PG8_BAR; PG8_WAIT_L(0); PG8_MMA(0, 1, At, B1); PG8_BAR;
;             PG8_LDA(At, 0, 1); PG8_STAGE(PG8_SA(0, 0), a2, voffA);
;             PG8_BAR; PG8_WAIT_L(0); PG8_MMA(1, 0, At, B0); PG8_BAR; PG8_SCHED;
.LBB0_275:
	s_ashr_i32 s13, s12, 31
	v_mov_b64_e32 v[0:1], 0x680
	s_lshl_b64 s[0:1], s[12:13], 19
	v_cmp_lt_i64_e32 vcc, s[16:17], v[0:1]
	s_add_u32 s16, s24, s0
	s_addc_u32 s17, s25, s1
	s_and_b64 s[0:1], vcc, exec
	s_cselect_b32 s0, s17, s9
	s_cselect_b32 s1, s16, s8
	s_ashr_i32 s15, s14, 31
	s_lshl_b64 s[18:19], s[14:15], 19
	s_add_u32 s36, s40, s18
	s_addc_u32 s37, s41, s19
	s_and_b64 s[18:19], vcc, exec
	s_cselect_b32 s5, s37, s47
	s_cselect_b32 s7, s36, s46
	s_add_u32 s8, s8, 0x40080
	s_addc_u32 s9, s9, 0
	s_add_u32 s13, s46, 0x100
	s_addc_u32 s15, s47, 0
	s_mov_b32 s18, -2
	s_cmp_eq_u32 s4, 12
	s_cbranch_scc1 .Lip13l_a_in
	s_add_u32 s19, s8, 0xfffc0080
	s_addc_u32 s26, s9, -1
	s_add_i32 s27, 0, 0x10000
	v_add_u32_e32 v8, s27, v214
	ds_read_b128 v[130:133], v8
	ds_read_b128 v[134:137], v8 offset:1024
	ds_read_b128 v[138:141], v8 offset:2048
	ds_read_b128 v[142:145], v8 offset:3072
	s_cmp_eq_u32 s18, 12
	s_cselect_b32 s69, s0, s26
	s_cselect_b32 s68, s1, s19
	s_cselect_b32 s47, s5, s15
	s_cselect_b32 s46, s7, s13
	v_lshl_add_u64 v[208:209], s[8:9], 0, v[184:185]
	s_add_i32 m0, s81, 0xc000
	ds_read_b128 v[146:149], v216
	ds_read_b128 v[150:153], v216 offset:1024
	ds_read_b128 v[188:191], v216 offset:2048
	ds_read_b128 v[192:195], v216 offset:3072
	ds_read_b128 v[196:199], v216 offset:4096
	ds_read_b128 v[200:203], v216 offset:5120
	ds_read_b128 v[204:207], v216 offset:6144
	ds_read_b128 v[218:221], v216 offset:7168
	global_load_lds_dwordx4 v[208:209], off
	s_add_i32 m0, s81, 0xe000
	v_lshl_add_u64 v[208:209], s[8:9], 0, v[186:187]
	global_load_lds_dwordx4 v[208:209], off
	s_waitcnt lgkmcnt(8)
	s_barrier
	s_waitcnt lgkmcnt(0)
	v_mfma_f32_16x16x32_bf16 v[126:129], v[130:133], v[146:149], 0
	v_mfma_f32_16x16x32_bf16 v[122:125], v[138:141], v[146:149], 0
	v_mfma_f32_16x16x32_bf16 v[114:117], v[130:133], v[188:191], 0
	v_mfma_f32_16x16x32_bf16 v[106:109], v[138:141], v[188:191], 0
	v_mfma_f32_16x16x32_bf16 v[94:97], v[130:133], v[196:199], 0
	v_mfma_f32_16x16x32_bf16 v[90:93], v[138:141], v[196:199], 0
	v_mfma_f32_16x16x32_bf16 v[82:85], v[130:133], v[204:207], 0
	v_mfma_f32_16x16x32_bf16 v[74:77], v[138:141], v[204:207], 0
	v_mfma_f32_16x16x32_bf16 v[126:129], v[134:137], v[150:153], v[126:129]
	v_mfma_f32_16x16x32_bf16 v[122:125], v[142:145], v[150:153], v[122:125]
	v_mfma_f32_16x16x32_bf16 v[114:117], v[134:137], v[192:195], v[114:117]
	v_mfma_f32_16x16x32_bf16 v[106:109], v[142:145], v[192:195], v[106:109]
	v_mfma_f32_16x16x32_bf16 v[94:97], v[134:137], v[200:203], v[94:97]
	v_mfma_f32_16x16x32_bf16 v[90:93], v[142:145], v[200:203], v[90:93]
	v_mfma_f32_16x16x32_bf16 v[82:85], v[134:137], v[218:221], v[82:85]
	v_mfma_f32_16x16x32_bf16 v[74:77], v[142:145], v[218:221], v[74:77]
	s_barrier
	s_add_i32 s19, 0, 0x14000
	s_add_i32 s26, s27, s80
	v_add_u32_e32 v8, s19, v214
	v_lshl_add_u64 v[208:209], s[46:47], 0, v[178:179]
	s_mov_b32 m0, s26
	ds_read_b128 v[222:225], v8
	ds_read_b128 v[226:229], v8 offset:1024
	ds_read_b128 v[230:233], v8 offset:2048
	ds_read_b128 v[234:237], v8 offset:3072
	global_load_lds_dwordx4 v[208:209], off
	s_add_i32 m0, s26, 0x2000
	v_lshl_add_u64 v[238:239], s[46:47], 0, v[182:183]
	global_load_lds_dwordx4 v[238:239], off
	s_barrier
	s_waitcnt lgkmcnt(0)
	v_mfma_f32_16x16x32_bf16 v[118:121], v[222:225], v[146:149], 0
	v_mfma_f32_16x16x32_bf16 v[110:113], v[230:233], v[146:149], 0
	v_mfma_f32_16x16x32_bf16 v[102:105], v[222:225], v[188:191], 0
	v_mfma_f32_16x16x32_bf16 v[98:101], v[230:233], v[188:191], 0
	v_mfma_f32_16x16x32_bf16 v[86:89], v[222:225], v[196:199], 0
	v_mfma_f32_16x16x32_bf16 v[78:81], v[230:233], v[196:199], 0
	v_mfma_f32_16x16x32_bf16 v[62:65], v[222:225], v[204:207], 0
	v_mfma_f32_16x16x32_bf16 v[58:61], v[230:233], v[204:207], 0
	v_mfma_f32_16x16x32_bf16 v[118:121], v[226:229], v[150:153], v[118:121]
	v_mfma_f32_16x16x32_bf16 v[110:113], v[234:237], v[150:153], v[110:113]
	v_mfma_f32_16x16x32_bf16 v[102:105], v[226:229], v[192:195], v[102:105]
	v_mfma_f32_16x16x32_bf16 v[98:101], v[234:237], v[192:195], v[98:101]
	v_mfma_f32_16x16x32_bf16 v[86:89], v[226:229], v[200:203], v[86:89]
	v_mfma_f32_16x16x32_bf16 v[78:81], v[234:237], v[200:203], v[78:81]
	v_mfma_f32_16x16x32_bf16 v[62:65], v[226:229], v[218:221], v[62:65]
	v_mfma_f32_16x16x32_bf16 v[58:61], v[234:237], v[218:221], v[58:61]
	s_mov_b32 m0, s81
	v_lshl_add_u64 v[240:241], s[68:69], 0, v[176:177]
	s_barrier
	ds_read_b128 v[146:149], v216 offset:16384
	ds_read_b128 v[150:153], v216 offset:17408
	ds_read_b128 v[188:191], v216 offset:18432
	ds_read_b128 v[192:195], v216 offset:19456
	ds_read_b128 v[196:199], v216 offset:20480
	ds_read_b128 v[200:203], v216 offset:21504
	ds_read_b128 v[204:207], v216 offset:22528
	ds_read_b128 v[218:221], v216 offset:23552
	global_load_lds_dwordx4 v[240:241], off
	s_mov_b32 m0, s82
	v_lshl_add_u64 v[242:243], s[68:69], 0, v[180:181]
	global_load_lds_dwordx4 v[242:243], off
	s_barrier
	s_waitcnt lgkmcnt(0)
	v_mfma_f32_16x16x32_bf16 v[70:73], v[130:133], v[146:149], 0
	v_mfma_f32_16x16x32_bf16 v[66:69], v[138:141], v[146:149], 0
	v_mfma_f32_16x16x32_bf16 v[46:49], v[130:133], v[188:191], 0
	v_mfma_f32_16x16x32_bf16 v[42:45], v[138:141], v[188:191], 0
	v_mfma_f32_16x16x32_bf16 v[30:33], v[130:133], v[196:199], 0
	v_mfma_f32_16x16x32_bf16 v[26:29], v[138:141], v[196:199], 0
	v_mfma_f32_16x16x32_bf16 v[14:17], v[130:133], v[204:207], 0
	v_mfma_f32_16x16x32_bf16 v[10:13], v[138:141], v[204:207], 0
	v_mfma_f32_16x16x32_bf16 v[70:73], v[134:137], v[150:153], v[70:73]
	v_mfma_f32_16x16x32_bf16 v[66:69], v[142:145], v[150:153], v[66:69]
	v_mfma_f32_16x16x32_bf16 v[46:49], v[134:137], v[192:195], v[46:49]
	v_mfma_f32_16x16x32_bf16 v[42:45], v[142:145], v[192:195], v[42:45]
	v_mfma_f32_16x16x32_bf16 v[30:33], v[134:137], v[200:203], v[30:33]
	v_mfma_f32_16x16x32_bf16 v[26:29], v[142:145], v[200:203], v[26:29]
	v_mfma_f32_16x16x32_bf16 v[14:17], v[134:137], v[218:221], v[14:17]
	v_mfma_f32_16x16x32_bf16 v[10:13], v[142:145], v[218:221], v[10:13]
	s_barrier
; #define PG8_STAGE(bufoff, gbase, voff) do { _Pragma("unroll") for (int _i = 0; _i < 2; ++_i) \
;         __builtin_amdgcn_global_load_lds((const unsigned*)((const char*)(gbase) + (voff)[_i]), (LAS unsigned*)(lds + (bufoff) + ldsw + _i * 8192), 16, 0, 0); } while (0)
; #define PG8_LDA(dst, b, h) do { _Pragma("unroll") for (int m = 0; m < 4; ++m) _Pragma("unroll") for (int k = 0; k < 2; ++k) dst[m][k] = *(const LAS bf16x8*)(lds + PG8_SA(b, h) + aoff + m * 2048 + k * 1024); } while (0)
; #define PG8_LDB(dst, b, h) do { _Pragma("unroll") for (int n = 0; n < 2; ++n) _Pragma("unroll") for (int k = 0; k < 2; ++k) dst[n][k] = *(const LAS bf16x8*)(lds + PG8_SB(b, h) + boff + n * 2048 + k * 1024); } while (0)
; #define PG8_MMA(ai, bj, At, Bt) do { __builtin_amdgcn_s_setprio(1); _Pragma("unroll") for (int m = 0; m < 4; ++m) _Pragma("unroll") for (int n = 0; n < 2; ++n) _Pragma("unroll") for (int k = 0; k < 2; ++k) \
;         acc[ai][bj][m][n] = __builtin_amdgcn_mfma_f32_16x16x32_bf16(Bt[n][k], At[m][k], acc[ai][bj][m][n], 0, 0, 0); __builtin_amdgcn_s_setprio(0); } while (0)
; #define PG8_WAIT_V(n) asm volatile("s_waitcnt vmcnt(" #n ")" ::: "memory")
; #define PG8_WAIT_L(n) asm volatile("s_waitcnt lgkmcnt(" #n ")" ::: "memory")
; #define PG8_BAR __builtin_amdgcn_s_barrier()
; #define PG8_SCHED __builtin_amdgcn_sched_barrier(0)
; template <class Epi>
; DEVI void gemm_phase(LAS unsigned char* lds, const Gemm g, const Epi& E) {
;     ...
;             PG8_STAGE(PG8_SB(0, 1), b2 + hstepB, voffB);
;             PG8_WAIT_V(6); PG8_BAR; PG8_MMA(1, 1, At, B1); PG8_BAR;
;             PG8_LDB(B0, 1, 0); PG8_SCHED; PG8_LDA(At, 1, 0); PG8_STAGE(PG8_SA(0, 1), a2 + hstepA, voffA);
;             PG8_WAIT_L(8); PG8_BAR; PG8_WAIT_L(0); PG8_MMA(0, 0, At, B0); PG8_BAR; PG8_SCHED;
;             PG8_LDB(B1, 1, 1); PG8_STAGE(PG8_SB(1, 0), b3, voffB);
;             PG8_BAR; PG8_WAIT_L(0); PG8_MMA(0, 1, At, B1); PG8_BAR;
;             PG8_LDA(At, 1, 1); PG8_STAGE(PG8_SA(1, 0), a3, voffA);
	s_add_u32 s26, s46, 0x40000
	s_addc_u32 s27, s47, 0
	s_add_i32 s19, s19, s80
	s_mov_b32 m0, s19
	v_lshl_add_u64 v[130:131], s[26:27], 0, v[178:179]
	global_load_lds_dwordx4 v[130:131], off
	s_add_i32 m0, s19, 0x2000
	v_lshl_add_u64 v[130:131], s[26:27], 0, v[182:183]
	global_load_lds_dwordx4 v[130:131], off
	s_waitcnt vmcnt(6)
	s_barrier
	v_mfma_f32_16x16x32_bf16 v[50:53], v[222:225], v[146:149], 0
	v_mfma_f32_16x16x32_bf16 v[54:57], v[230:233], v[146:149], 0
	v_mfma_f32_16x16x32_bf16 v[34:37], v[222:225], v[188:191], 0
	v_mfma_f32_16x16x32_bf16 v[38:41], v[230:233], v[188:191], 0
	v_mfma_f32_16x16x32_bf16 v[18:21], v[222:225], v[196:199], 0
	v_mfma_f32_16x16x32_bf16 v[22:25], v[230:233], v[196:199], 0
	v_mfma_f32_16x16x32_bf16 v[0:3], v[222:225], v[204:207], 0
	v_mfma_f32_16x16x32_bf16 v[4:7], v[230:233], v[204:207], 0
	v_mfma_f32_16x16x32_bf16 v[50:53], v[226:229], v[150:153], v[50:53]
	v_mfma_f32_16x16x32_bf16 v[54:57], v[234:237], v[150:153], v[54:57]
	v_mfma_f32_16x16x32_bf16 v[34:37], v[226:229], v[192:195], v[34:37]
	v_mfma_f32_16x16x32_bf16 v[38:41], v[234:237], v[192:195], v[38:41]
	v_mfma_f32_16x16x32_bf16 v[18:21], v[226:229], v[200:203], v[18:21]
	v_mfma_f32_16x16x32_bf16 v[22:25], v[234:237], v[200:203], v[22:25]
	v_mfma_f32_16x16x32_bf16 v[0:3], v[226:229], v[218:221], v[0:3]
	v_mfma_f32_16x16x32_bf16 v[4:7], v[234:237], v[218:221], v[4:7]
	s_add_i32 s19, 0, 0x18000
	v_add_u32_e32 v8, s19, v214
	s_barrier
	ds_read_b128 v[130:133], v8
	ds_read_b128 v[134:137], v8 offset:1024
	ds_read_b128 v[138:141], v8 offset:2048
	ds_read_b128 v[142:145], v8 offset:3072
	s_add_u32 s26, s68, 0x40000
	s_addc_u32 s27, s69, 0
	s_mov_b32 m0, s83
	v_lshl_add_u64 v[222:223], s[26:27], 0, v[176:177]
	ds_read_b128 v[146:149], v216 offset:32768
	ds_read_b128 v[150:153], v216 offset:33792
	ds_read_b128 v[188:191], v216 offset:34816
	ds_read_b128 v[192:195], v216 offset:35840
	ds_read_b128 v[196:199], v216 offset:36864
	ds_read_b128 v[200:203], v216 offset:37888
	ds_read_b128 v[204:207], v216 offset:38912
	ds_read_b128 v[218:221], v216 offset:39936
	global_load_lds_dwordx4 v[222:223], off
	s_mov_b32 m0, s84
	v_lshl_add_u64 v[222:223], s[26:27], 0, v[180:181]
	global_load_lds_dwordx4 v[222:223], off
	s_waitcnt lgkmcnt(8)
	s_barrier
	s_waitcnt lgkmcnt(0)
	v_mfma_f32_16x16x32_bf16 v[126:129], v[130:133], v[146:149], v[126:129]
	v_mfma_f32_16x16x32_bf16 v[122:125], v[138:141], v[146:149], v[122:125]
	v_mfma_f32_16x16x32_bf16 v[114:117], v[130:133], v[188:191], v[114:117]
	v_mfma_f32_16x16x32_bf16 v[106:109], v[138:141], v[188:191], v[106:109]
	v_mfma_f32_16x16x32_bf16 v[94:97], v[130:133], v[196:199], v[94:97]
	v_mfma_f32_16x16x32_bf16 v[90:93], v[138:141], v[196:199], v[90:93]
	v_mfma_f32_16x16x32_bf16 v[82:85], v[130:133], v[204:207], v[82:85]
	v_mfma_f32_16x16x32_bf16 v[74:77], v[138:141], v[204:207], v[74:77]
	v_mfma_f32_16x16x32_bf16 v[126:129], v[134:137], v[150:153], v[126:129]
	v_mfma_f32_16x16x32_bf16 v[122:125], v[142:145], v[150:153], v[122:125]
	v_mfma_f32_16x16x32_bf16 v[114:117], v[134:137], v[192:195], v[114:117]
	v_mfma_f32_16x16x32_bf16 v[106:109], v[142:145], v[192:195], v[106:109]
	v_mfma_f32_16x16x32_bf16 v[94:97], v[134:137], v[200:203], v[94:97]
	v_mfma_f32_16x16x32_bf16 v[90:93], v[142:145], v[200:203], v[90:93]
	v_mfma_f32_16x16x32_bf16 v[82:85], v[134:137], v[218:221], v[82:85]
	v_mfma_f32_16x16x32_bf16 v[74:77], v[142:145], v[218:221], v[74:77]
	s_barrier
	s_add_i32 s38, 0, 0x1c000
	s_add_i32 s19, s19, s80
	v_add_u32_e32 v8, s38, v214
	v_lshl_add_u64 v[208:209], v[208:209], 0, s[70:71]
	s_mov_b32 m0, s19
	ds_read_b128 v[222:225], v8
	ds_read_b128 v[226:229], v8 offset:1024
	ds_read_b128 v[230:233], v8 offset:2048
	ds_read_b128 v[234:237], v8 offset:3072
	global_load_lds_dwordx4 v[208:209], off
	s_add_i32 m0, s19, 0x2000
	v_lshl_add_u64 v[208:209], v[238:239], 0, s[70:71]
	global_load_lds_dwordx4 v[208:209], off
	s_barrier
	s_waitcnt lgkmcnt(0)
	v_mfma_f32_16x16x32_bf16 v[118:121], v[222:225], v[146:149], v[118:121]
	v_mfma_f32_16x16x32_bf16 v[110:113], v[230:233], v[146:149], v[110:113]
	v_mfma_f32_16x16x32_bf16 v[102:105], v[222:225], v[188:191], v[102:105]
	v_mfma_f32_16x16x32_bf16 v[98:101], v[230:233], v[188:191], v[98:101]
	v_mfma_f32_16x16x32_bf16 v[86:89], v[222:225], v[196:199], v[86:89]
	v_mfma_f32_16x16x32_bf16 v[78:81], v[230:233], v[196:199], v[78:81]
	v_mfma_f32_16x16x32_bf16 v[62:65], v[222:225], v[204:207], v[62:65]
	v_mfma_f32_16x16x32_bf16 v[58:61], v[230:233], v[204:207], v[58:61]
	v_mfma_f32_16x16x32_bf16 v[118:121], v[226:229], v[150:153], v[118:121]
	v_mfma_f32_16x16x32_bf16 v[110:113], v[234:237], v[150:153], v[110:113]
	v_mfma_f32_16x16x32_bf16 v[102:105], v[226:229], v[192:195], v[102:105]
	v_mfma_f32_16x16x32_bf16 v[98:101], v[234:237], v[192:195], v[98:101]
	v_mfma_f32_16x16x32_bf16 v[86:89], v[226:229], v[200:203], v[86:89]
	v_mfma_f32_16x16x32_bf16 v[78:81], v[234:237], v[200:203], v[78:81]
	v_mfma_f32_16x16x32_bf16 v[62:65], v[226:229], v[218:221], v[62:65]
	v_mfma_f32_16x16x32_bf16 v[58:61], v[234:237], v[218:221], v[58:61]
	s_mov_b32 m0, s85
	v_lshl_add_u64 v[208:209], v[240:241], 0, s[70:71]
	s_barrier
	ds_read_b128 v[146:149], v216 offset:49152
	ds_read_b128 v[150:153], v216 offset:50176
	ds_read_b128 v[188:191], v216 offset:51200
	ds_read_b128 v[192:195], v216 offset:52224
	ds_read_b128 v[196:199], v216 offset:53248
	ds_read_b128 v[200:203], v216 offset:54272
	ds_read_b128 v[204:207], v216 offset:55296
	ds_read_b128 v[218:221], v216 offset:56320
	global_load_lds_dwordx4 v[208:209], off
	s_mov_b32 m0, s86
	v_lshl_add_u64 v[208:209], v[242:243], 0, s[70:71]
	global_load_lds_dwordx4 v[208:209], off
	s_barrier
; #define PG8_STAGE(bufoff, gbase, voff) do { _Pragma("unroll") for (int _i = 0; _i < 2; ++_i) \
;         __builtin_amdgcn_global_load_lds((const unsigned*)((const char*)(gbase) + (voff)[_i]), (LAS unsigned*)(lds + (bufoff) + ldsw + _i * 8192), 16, 0, 0); } while (0)
; #define PG8_LDA(dst, b, h) do { _Pragma("unroll") for (int m = 0; m < 4; ++m) _Pragma("unroll") for (int k = 0; k < 2; ++k) dst[m][k] = *(const LAS bf16x8*)(lds + PG8_SA(b, h) + aoff + m * 2048 + k * 1024); } while (0)
; #define PG8_WAIT_V(n) asm volatile("s_waitcnt vmcnt(" #n ")" ::: "memory")
; #define PG8_WAIT_L(n) asm volatile("s_waitcnt lgkmcnt(" #n ")" ::: "memory")
; #define PG8_BAR __builtin_amdgcn_s_barrier()
; template <class Epi>
; DEVI void gemm_phase(LAS unsigned char* lds, const Gemm g, const Epi& E) {
;     ...
;         for (int t = 0; t < nt; t += 2) {
;             const bool last = (t == nt - 2);
;             const char* a1 = cA + (size_t)(t + 1) * kstep;
;             const char* a2 = last ? nA : cA + (size_t)(t + 2) * kstep; const char* b2 = last ? nB : cB + (size_t)(t + 2) * kstep;
;             const char* a3 = a2 + kstep; const char* b3 = b2 + kstep;
;             PG8_LDB(B0, 0, 0); PG8_SCHED; PG8_LDA(At, 0, 0); PG8_STAGE(PG8_SA(1, 1), a1 + hstepA, voffA);
;             PG8_WAIT_L(8); PG8_BAR; PG8_WAIT_L(0); PG8_MMA(0, 0, At, B0); PG8_BAR; PG8_SCHED;
;             PG8_LDB(B1, 0, 1); PG8_STAGE(PG8_SB(0, 0), b2, voffB);
;             PG8_BAR; PG8_WAIT_L(0); PG8_MMA(0, 1, At, B1); PG8_BAR;
;             PG8_LDA(At, 0, 1); PG8_STAGE(PG8_SA(0, 0), a2, voffA);
;             PG8_BAR; PG8_WAIT_L(0); PG8_MMA(1, 0, At, B0); PG8_BAR; PG8_SCHED;
;             PG8_STAGE(PG8_SB(0, 1), b2 + hstepB, voffB);
;             PG8_WAIT_V(6); PG8_BAR; PG8_MMA(1, 1, At, B1); PG8_BAR;
;             PG8_LDB(B0, 1, 0); PG8_SCHED; PG8_LDA(At, 1, 0); PG8_STAGE(PG8_SA(0, 1), a2 + hstepA, voffA);
;             PG8_WAIT_L(8); PG8_BAR; PG8_WAIT_L(0); PG8_MMA(0, 0, At, B0); PG8_BAR; PG8_SCHED;
;             PG8_LDB(B1, 1, 1); PG8_STAGE(PG8_SB(1, 0), b3, voffB);
;             PG8_BAR; PG8_WAIT_L(0); PG8_MMA(0, 1, At, B1); PG8_BAR;
;             PG8_LDA(At, 1, 1); PG8_STAGE(PG8_SA(1, 0), a3, voffA);
;             PG8_BAR; PG8_WAIT_L(0); PG8_MMA(1, 0, At, B0); PG8_BAR; PG8_SCHED;
;             PG8_STAGE(PG8_SB(1, 1), b3 + hstepB, voffB);
;             PG8_WAIT_V(6); PG8_BAR; PG8_MMA(1, 1, At, B1); PG8_BAR;
	s_waitcnt lgkmcnt(0)
	v_mfma_f32_16x16x32_bf16 v[70:73], v[130:133], v[146:149], v[70:73]
	v_mfma_f32_16x16x32_bf16 v[66:69], v[138:141], v[146:149], v[66:69]
	v_mfma_f32_16x16x32_bf16 v[46:49], v[130:133], v[188:191], v[46:49]
	v_mfma_f32_16x16x32_bf16 v[42:45], v[138:141], v[188:191], v[42:45]
	v_mfma_f32_16x16x32_bf16 v[30:33], v[130:133], v[196:199], v[30:33]
	v_mfma_f32_16x16x32_bf16 v[26:29], v[138:141], v[196:199], v[26:29]
	v_mfma_f32_16x16x32_bf16 v[14:17], v[130:133], v[204:207], v[14:17]
	v_mfma_f32_16x16x32_bf16 v[10:13], v[138:141], v[204:207], v[10:13]
	v_mfma_f32_16x16x32_bf16 v[70:73], v[134:137], v[150:153], v[70:73]
	v_mfma_f32_16x16x32_bf16 v[66:69], v[142:145], v[150:153], v[66:69]
	v_mfma_f32_16x16x32_bf16 v[46:49], v[134:137], v[192:195], v[46:49]
	v_mfma_f32_16x16x32_bf16 v[42:45], v[142:145], v[192:195], v[42:45]
	v_mfma_f32_16x16x32_bf16 v[30:33], v[134:137], v[200:203], v[30:33]
	v_mfma_f32_16x16x32_bf16 v[26:29], v[142:145], v[200:203], v[26:29]
	v_mfma_f32_16x16x32_bf16 v[14:17], v[134:137], v[218:221], v[14:17]
	v_mfma_f32_16x16x32_bf16 v[10:13], v[142:145], v[218:221], v[10:13]
	s_barrier
	s_add_u32 s26, s46, 0x40080
	s_addc_u32 s27, s47, 0
	s_add_i32 s19, s38, s80
	s_mov_b32 m0, s19
	v_lshl_add_u64 v[130:131], s[26:27], 0, v[178:179]
	global_load_lds_dwordx4 v[130:131], off
	s_add_i32 m0, s19, 0x2000
	v_lshl_add_u64 v[130:131], s[26:27], 0, v[182:183]
	global_load_lds_dwordx4 v[130:131], off
	s_waitcnt vmcnt(6)
	s_barrier
	v_mfma_f32_16x16x32_bf16 v[50:53], v[222:225], v[146:149], v[50:53]
	v_mfma_f32_16x16x32_bf16 v[54:57], v[230:233], v[146:149], v[54:57]
	v_mfma_f32_16x16x32_bf16 v[34:37], v[222:225], v[188:191], v[34:37]
	v_mfma_f32_16x16x32_bf16 v[38:41], v[230:233], v[188:191], v[38:41]
	v_mfma_f32_16x16x32_bf16 v[18:21], v[222:225], v[196:199], v[18:21]
	v_mfma_f32_16x16x32_bf16 v[22:25], v[230:233], v[196:199], v[22:25]
	v_mfma_f32_16x16x32_bf16 v[0:3], v[222:225], v[204:207], v[0:3]
	v_mfma_f32_16x16x32_bf16 v[4:7], v[230:233], v[204:207], v[4:7]
	v_mfma_f32_16x16x32_bf16 v[50:53], v[226:229], v[150:153], v[50:53]
	v_mfma_f32_16x16x32_bf16 v[54:57], v[234:237], v[150:153], v[54:57]
	v_mfma_f32_16x16x32_bf16 v[34:37], v[226:229], v[192:195], v[34:37]
	v_mfma_f32_16x16x32_bf16 v[38:41], v[234:237], v[192:195], v[38:41]
	v_mfma_f32_16x16x32_bf16 v[18:21], v[226:229], v[200:203], v[18:21]
	v_mfma_f32_16x16x32_bf16 v[22:25], v[234:237], v[200:203], v[22:25]
	v_mfma_f32_16x16x32_bf16 v[0:3], v[226:229], v[218:221], v[0:3]
	v_mfma_f32_16x16x32_bf16 v[4:7], v[234:237], v[218:221], v[4:7]
	s_add_i32 s18, s18, 2
	s_add_u32 s8, s8, 0x100
	s_addc_u32 s9, s9, 0
	s_add_u32 s13, s13, 0x100
	s_addc_u32 s15, s15, 0
	s_cmp_gt_u32 s18, 13
	s_barrier
.LBB0_276:
	s_add_u32 s19, s8, 0xfffc0080
	s_addc_u32 s26, s9, -1
	s_add_i32 s27, 0, 0x10000
	v_add_u32_e32 v8, s27, v214
	ds_read_b128 v[130:133], v8
	ds_read_b128 v[134:137], v8 offset:1024
	ds_read_b128 v[138:141], v8 offset:2048
	ds_read_b128 v[142:145], v8 offset:3072
	s_cmp_eq_u32 s18, 12
	s_cselect_b32 s69, s0, s26
	s_cselect_b32 s68, s1, s19
	s_cselect_b32 s47, s5, s15
	s_cselect_b32 s46, s7, s13
	v_lshl_add_u64 v[208:209], s[8:9], 0, v[184:185]
	s_add_i32 m0, s81, 0xc000
	ds_read_b128 v[146:149], v216
	ds_read_b128 v[150:153], v216 offset:1024
	ds_read_b128 v[188:191], v216 offset:2048
	ds_read_b128 v[192:195], v216 offset:3072
	ds_read_b128 v[196:199], v216 offset:4096
	ds_read_b128 v[200:203], v216 offset:5120
	ds_read_b128 v[204:207], v216 offset:6144
	ds_read_b128 v[218:221], v216 offset:7168
	global_load_lds_dwordx4 v[208:209], off
	s_add_i32 m0, s81, 0xe000
	v_lshl_add_u64 v[208:209], s[8:9], 0, v[186:187]
	global_load_lds_dwordx4 v[208:209], off
	s_waitcnt lgkmcnt(8)
	s_barrier
	s_waitcnt lgkmcnt(0)
	v_mfma_f32_16x16x32_bf16 v[126:129], v[130:133], v[146:149], v[126:129]
	v_mfma_f32_16x16x32_bf16 v[122:125], v[138:141], v[146:149], v[122:125]
	v_mfma_f32_16x16x32_bf16 v[114:117], v[130:133], v[188:191], v[114:117]
	v_mfma_f32_16x16x32_bf16 v[106:109], v[138:141], v[188:191], v[106:109]
	v_mfma_f32_16x16x32_bf16 v[94:97], v[130:133], v[196:199], v[94:97]
	v_mfma_f32_16x16x32_bf16 v[90:93], v[138:141], v[196:199], v[90:93]
	v_mfma_f32_16x16x32_bf16 v[82:85], v[130:133], v[204:207], v[82:85]
	v_mfma_f32_16x16x32_bf16 v[74:77], v[138:141], v[204:207], v[74:77]
	v_mfma_f32_16x16x32_bf16 v[126:129], v[134:137], v[150:153], v[126:129]
	v_mfma_f32_16x16x32_bf16 v[122:125], v[142:145], v[150:153], v[122:125]
	v_mfma_f32_16x16x32_bf16 v[114:117], v[134:137], v[192:195], v[114:117]
	v_mfma_f32_16x16x32_bf16 v[106:109], v[142:145], v[192:195], v[106:109]
	v_mfma_f32_16x16x32_bf16 v[94:97], v[134:137], v[200:203], v[94:97]
	v_mfma_f32_16x16x32_bf16 v[90:93], v[142:145], v[200:203], v[90:93]
	v_mfma_f32_16x16x32_bf16 v[82:85], v[134:137], v[218:221], v[82:85]
	v_mfma_f32_16x16x32_bf16 v[74:77], v[142:145], v[218:221], v[74:77]
	s_barrier
	s_add_i32 s19, 0, 0x14000
	s_add_i32 s26, s27, s80
	v_add_u32_e32 v8, s19, v214
	v_lshl_add_u64 v[208:209], s[46:47], 0, v[178:179]
	s_mov_b32 m0, s26
	ds_read_b128 v[222:225], v8
	ds_read_b128 v[226:229], v8 offset:1024
	ds_read_b128 v[230:233], v8 offset:2048
	ds_read_b128 v[234:237], v8 offset:3072
	global_load_lds_dwordx4 v[208:209], off
	s_add_i32 m0, s26, 0x2000
	v_lshl_add_u64 v[238:239], s[46:47], 0, v[182:183]
	global_load_lds_dwordx4 v[238:239], off
	s_barrier
; #define PG8_STAGE(bufoff, gbase, voff) do { _Pragma("unroll") for (int _i = 0; _i < 2; ++_i) \
;         __builtin_amdgcn_global_load_lds((const unsigned*)((const char*)(gbase) + (voff)[_i]), (LAS unsigned*)(lds + (bufoff) + ldsw + _i * 8192), 16, 0, 0); } while (0)
; #define PG8_LDA(dst, b, h) do { _Pragma("unroll") for (int m = 0; m < 4; ++m) _Pragma("unroll") for (int k = 0; k < 2; ++k) dst[m][k] = *(const LAS bf16x8*)(lds + PG8_SA(b, h) + aoff + m * 2048 + k * 1024); } while (0)
; #define PG8_LDB(dst, b, h) do { _Pragma("unroll") for (int n = 0; n < 2; ++n) _Pragma("unroll") for (int k = 0; k < 2; ++k) dst[n][k] = *(const LAS bf16x8*)(lds + PG8_SB(b, h) + boff + n * 2048 + k * 1024); } while (0)
; #define PG8_MMA(ai, bj, At, Bt) do { __builtin_amdgcn_s_setprio(1); _Pragma("unroll") for (int m = 0; m < 4; ++m) _Pragma("unroll") for (int n = 0; n < 2; ++n) _Pragma("unroll") for (int k = 0; k < 2; ++k) \
;         acc[ai][bj][m][n] = __builtin_amdgcn_mfma_f32_16x16x32_bf16(Bt[n][k], At[m][k], acc[ai][bj][m][n], 0, 0, 0); __builtin_amdgcn_s_setprio(0); } while (0)
; #define PG8_WAIT_V(n) asm volatile("s_waitcnt vmcnt(" #n ")" ::: "memory")
; #define PG8_WAIT_L(n) asm volatile("s_waitcnt lgkmcnt(" #n ")" ::: "memory")
; #define PG8_BAR __builtin_amdgcn_s_barrier()
; #define PG8_SCHED __builtin_amdgcn_sched_barrier(0)
; template <class Epi>
; DEVI void gemm_phase(LAS unsigned char* lds, const Gemm g, const Epi& E) {
;     ...
;             PG8_BAR; PG8_WAIT_L(0); PG8_MMA(0, 1, At, B1); PG8_BAR;
;             PG8_LDA(At, 0, 1); PG8_STAGE(PG8_SA(0, 0), a2, voffA);
;             PG8_BAR; PG8_WAIT_L(0); PG8_MMA(1, 0, At, B0); PG8_BAR; PG8_SCHED;
;             PG8_STAGE(PG8_SB(0, 1), b2 + hstepB, voffB);
;             PG8_WAIT_V(6); PG8_BAR; PG8_MMA(1, 1, At, B1); PG8_BAR;
;             PG8_LDB(B0, 1, 0); PG8_SCHED; PG8_LDA(At, 1, 0); PG8_STAGE(PG8_SA(0, 1), a2 + hstepA, voffA);
	s_waitcnt lgkmcnt(0)
	v_mfma_f32_16x16x32_bf16 v[118:121], v[222:225], v[146:149], v[118:121]
	v_mfma_f32_16x16x32_bf16 v[110:113], v[230:233], v[146:149], v[110:113]
	v_mfma_f32_16x16x32_bf16 v[102:105], v[222:225], v[188:191], v[102:105]
	v_mfma_f32_16x16x32_bf16 v[98:101], v[230:233], v[188:191], v[98:101]
	v_mfma_f32_16x16x32_bf16 v[86:89], v[222:225], v[196:199], v[86:89]
	v_mfma_f32_16x16x32_bf16 v[78:81], v[230:233], v[196:199], v[78:81]
	v_mfma_f32_16x16x32_bf16 v[62:65], v[222:225], v[204:207], v[62:65]
	v_mfma_f32_16x16x32_bf16 v[58:61], v[230:233], v[204:207], v[58:61]
	v_mfma_f32_16x16x32_bf16 v[118:121], v[226:229], v[150:153], v[118:121]
	v_mfma_f32_16x16x32_bf16 v[110:113], v[234:237], v[150:153], v[110:113]
	v_mfma_f32_16x16x32_bf16 v[102:105], v[226:229], v[192:195], v[102:105]
	v_mfma_f32_16x16x32_bf16 v[98:101], v[234:237], v[192:195], v[98:101]
	v_mfma_f32_16x16x32_bf16 v[86:89], v[226:229], v[200:203], v[86:89]
	v_mfma_f32_16x16x32_bf16 v[78:81], v[234:237], v[200:203], v[78:81]
	v_mfma_f32_16x16x32_bf16 v[62:65], v[226:229], v[218:221], v[62:65]
	v_mfma_f32_16x16x32_bf16 v[58:61], v[234:237], v[218:221], v[58:61]
	s_mov_b32 m0, s81
	v_lshl_add_u64 v[240:241], s[68:69], 0, v[176:177]
	s_barrier
	ds_read_b128 v[146:149], v216 offset:16384
	ds_read_b128 v[150:153], v216 offset:17408
	ds_read_b128 v[188:191], v216 offset:18432
	ds_read_b128 v[192:195], v216 offset:19456
	ds_read_b128 v[196:199], v216 offset:20480
	ds_read_b128 v[200:203], v216 offset:21504
	ds_read_b128 v[204:207], v216 offset:22528
	ds_read_b128 v[218:221], v216 offset:23552
	global_load_lds_dwordx4 v[240:241], off
	s_mov_b32 m0, s82
	v_lshl_add_u64 v[242:243], s[68:69], 0, v[180:181]
	global_load_lds_dwordx4 v[242:243], off
	s_barrier
	s_waitcnt lgkmcnt(0)
	v_mfma_f32_16x16x32_bf16 v[70:73], v[130:133], v[146:149], v[70:73]
	v_mfma_f32_16x16x32_bf16 v[66:69], v[138:141], v[146:149], v[66:69]
	v_mfma_f32_16x16x32_bf16 v[46:49], v[130:133], v[188:191], v[46:49]
	v_mfma_f32_16x16x32_bf16 v[42:45], v[138:141], v[188:191], v[42:45]
	v_mfma_f32_16x16x32_bf16 v[30:33], v[130:133], v[196:199], v[30:33]
	v_mfma_f32_16x16x32_bf16 v[26:29], v[138:141], v[196:199], v[26:29]
	v_mfma_f32_16x16x32_bf16 v[14:17], v[130:133], v[204:207], v[14:17]
	v_mfma_f32_16x16x32_bf16 v[10:13], v[138:141], v[204:207], v[10:13]
	v_mfma_f32_16x16x32_bf16 v[70:73], v[134:137], v[150:153], v[70:73]
	v_mfma_f32_16x16x32_bf16 v[66:69], v[142:145], v[150:153], v[66:69]
	v_mfma_f32_16x16x32_bf16 v[46:49], v[134:137], v[192:195], v[46:49]
	v_mfma_f32_16x16x32_bf16 v[42:45], v[142:145], v[192:195], v[42:45]
	v_mfma_f32_16x16x32_bf16 v[30:33], v[134:137], v[200:203], v[30:33]
	v_mfma_f32_16x16x32_bf16 v[26:29], v[142:145], v[200:203], v[26:29]
	v_mfma_f32_16x16x32_bf16 v[14:17], v[134:137], v[218:221], v[14:17]
	v_mfma_f32_16x16x32_bf16 v[10:13], v[142:145], v[218:221], v[10:13]
	s_barrier
	s_add_u32 s26, s46, 0x40000
	s_addc_u32 s27, s47, 0
	s_add_i32 s19, s19, s80
	s_mov_b32 m0, s19
	v_lshl_add_u64 v[130:131], s[26:27], 0, v[178:179]
	global_load_lds_dwordx4 v[130:131], off
	s_add_i32 m0, s19, 0x2000
	v_lshl_add_u64 v[130:131], s[26:27], 0, v[182:183]
	global_load_lds_dwordx4 v[130:131], off
	s_waitcnt vmcnt(6)
	s_barrier
	v_mfma_f32_16x16x32_bf16 v[50:53], v[222:225], v[146:149], v[50:53]
	v_mfma_f32_16x16x32_bf16 v[54:57], v[230:233], v[146:149], v[54:57]
	v_mfma_f32_16x16x32_bf16 v[34:37], v[222:225], v[188:191], v[34:37]
	v_mfma_f32_16x16x32_bf16 v[38:41], v[230:233], v[188:191], v[38:41]
	v_mfma_f32_16x16x32_bf16 v[18:21], v[222:225], v[196:199], v[18:21]
	v_mfma_f32_16x16x32_bf16 v[22:25], v[230:233], v[196:199], v[22:25]
	v_mfma_f32_16x16x32_bf16 v[0:3], v[222:225], v[204:207], v[0:3]
	v_mfma_f32_16x16x32_bf16 v[4:7], v[230:233], v[204:207], v[4:7]
	v_mfma_f32_16x16x32_bf16 v[50:53], v[226:229], v[150:153], v[50:53]
	v_mfma_f32_16x16x32_bf16 v[54:57], v[234:237], v[150:153], v[54:57]
	v_mfma_f32_16x16x32_bf16 v[34:37], v[226:229], v[192:195], v[34:37]
	v_mfma_f32_16x16x32_bf16 v[38:41], v[234:237], v[192:195], v[38:41]
	v_mfma_f32_16x16x32_bf16 v[18:21], v[226:229], v[200:203], v[18:21]
	v_mfma_f32_16x16x32_bf16 v[22:25], v[234:237], v[200:203], v[22:25]
	v_mfma_f32_16x16x32_bf16 v[0:3], v[226:229], v[218:221], v[0:3]
	v_mfma_f32_16x16x32_bf16 v[4:7], v[234:237], v[218:221], v[4:7]
	s_add_i32 s19, 0, 0x18000
	v_add_u32_e32 v8, s19, v214
	s_barrier
	ds_read_b128 v[130:133], v8
	ds_read_b128 v[134:137], v8 offset:1024
	ds_read_b128 v[138:141], v8 offset:2048
	ds_read_b128 v[142:145], v8 offset:3072
	s_add_u32 s26, s68, 0x40000
	s_addc_u32 s27, s69, 0
	s_mov_b32 m0, s83
	v_lshl_add_u64 v[222:223], s[26:27], 0, v[176:177]
	ds_read_b128 v[146:149], v216 offset:32768
	ds_read_b128 v[150:153], v216 offset:33792
	ds_read_b128 v[188:191], v216 offset:34816
	ds_read_b128 v[192:195], v216 offset:35840
	ds_read_b128 v[196:199], v216 offset:36864
	ds_read_b128 v[200:203], v216 offset:37888
	ds_read_b128 v[204:207], v216 offset:38912
	ds_read_b128 v[218:221], v216 offset:39936
	global_load_lds_dwordx4 v[222:223], off
	s_mov_b32 m0, s84
	v_lshl_add_u64 v[222:223], s[26:27], 0, v[180:181]
	global_load_lds_dwordx4 v[222:223], off
	s_waitcnt lgkmcnt(8)
	s_barrier
; #define PG8_STAGE(bufoff, gbase, voff) do { _Pragma("unroll") for (int _i = 0; _i < 2; ++_i) \
;         __builtin_amdgcn_global_load_lds((const unsigned*)((const char*)(gbase) + (voff)[_i]), (LAS unsigned*)(lds + (bufoff) + ldsw + _i * 8192), 16, 0, 0); } while (0)
; #define PG8_LDA(dst, b, h) do { _Pragma("unroll") for (int m = 0; m < 4; ++m) _Pragma("unroll") for (int k = 0; k < 2; ++k) dst[m][k] = *(const LAS bf16x8*)(lds + PG8_SA(b, h) + aoff + m * 2048 + k * 1024); } while (0)
; #define PG8_LDB(dst, b, h) do { _Pragma("unroll") for (int n = 0; n < 2; ++n) _Pragma("unroll") for (int k = 0; k < 2; ++k) dst[n][k] = *(const LAS bf16x8*)(lds + PG8_SB(b, h) + boff + n * 2048 + k * 1024); } while (0)
; #define PG8_MMA(ai, bj, At, Bt) do { __builtin_amdgcn_s_setprio(1); _Pragma("unroll") for (int m = 0; m < 4; ++m) _Pragma("unroll") for (int n = 0; n < 2; ++n) _Pragma("unroll") for (int k = 0; k < 2; ++k) \
;         acc[ai][bj][m][n] = __builtin_amdgcn_mfma_f32_16x16x32_bf16(Bt[n][k], At[m][k], acc[ai][bj][m][n], 0, 0, 0); __builtin_amdgcn_s_setprio(0); } while (0)
; #define PG8_WAIT_V(n) asm volatile("s_waitcnt vmcnt(" #n ")" ::: "memory")
; #define PG8_WAIT_L(n) asm volatile("s_waitcnt lgkmcnt(" #n ")" ::: "memory")
; #define PG8_BAR __builtin_amdgcn_s_barrier()
; #define PG8_SCHED __builtin_amdgcn_sched_barrier(0)
; template <class Epi>
; DEVI void gemm_phase(LAS unsigned char* lds, const Gemm g, const Epi& E) {
;     ...
;             PG8_WAIT_L(8); PG8_BAR; PG8_WAIT_L(0); PG8_MMA(0, 0, At, B0); PG8_BAR; PG8_SCHED;
;             PG8_LDB(B1, 1, 1); PG8_STAGE(PG8_SB(1, 0), b3, voffB);
;             PG8_BAR; PG8_WAIT_L(0); PG8_MMA(0, 1, At, B1); PG8_BAR;
;             PG8_LDA(At, 1, 1); PG8_STAGE(PG8_SA(1, 0), a3, voffA);
;             PG8_BAR; PG8_WAIT_L(0); PG8_MMA(1, 0, At, B0); PG8_BAR; PG8_SCHED;
;             PG8_STAGE(PG8_SB(1, 1), b3 + hstepB, voffB);
;             PG8_WAIT_V(6); PG8_BAR; PG8_MMA(1, 1, At, B1); PG8_BAR;
;         }
	s_waitcnt lgkmcnt(0)
	v_mfma_f32_16x16x32_bf16 v[126:129], v[130:133], v[146:149], v[126:129]
	v_mfma_f32_16x16x32_bf16 v[122:125], v[138:141], v[146:149], v[122:125]
	v_mfma_f32_16x16x32_bf16 v[114:117], v[130:133], v[188:191], v[114:117]
	v_mfma_f32_16x16x32_bf16 v[106:109], v[138:141], v[188:191], v[106:109]
	v_mfma_f32_16x16x32_bf16 v[94:97], v[130:133], v[196:199], v[94:97]
	v_mfma_f32_16x16x32_bf16 v[90:93], v[138:141], v[196:199], v[90:93]
	v_mfma_f32_16x16x32_bf16 v[82:85], v[130:133], v[204:207], v[82:85]
	v_mfma_f32_16x16x32_bf16 v[74:77], v[138:141], v[204:207], v[74:77]
	v_mfma_f32_16x16x32_bf16 v[126:129], v[134:137], v[150:153], v[126:129]
	v_mfma_f32_16x16x32_bf16 v[122:125], v[142:145], v[150:153], v[122:125]
	v_mfma_f32_16x16x32_bf16 v[114:117], v[134:137], v[192:195], v[114:117]
	v_mfma_f32_16x16x32_bf16 v[106:109], v[142:145], v[192:195], v[106:109]
	v_mfma_f32_16x16x32_bf16 v[94:97], v[134:137], v[200:203], v[94:97]
	v_mfma_f32_16x16x32_bf16 v[90:93], v[142:145], v[200:203], v[90:93]
	v_mfma_f32_16x16x32_bf16 v[82:85], v[134:137], v[218:221], v[82:85]
	v_mfma_f32_16x16x32_bf16 v[74:77], v[142:145], v[218:221], v[74:77]
	s_barrier
	s_add_i32 s38, 0, 0x1c000
	s_add_i32 s19, s19, s80
	v_add_u32_e32 v8, s38, v214
	v_lshl_add_u64 v[208:209], v[208:209], 0, s[70:71]
	s_mov_b32 m0, s19
	ds_read_b128 v[222:225], v8
	ds_read_b128 v[226:229], v8 offset:1024
	ds_read_b128 v[230:233], v8 offset:2048
	ds_read_b128 v[234:237], v8 offset:3072
	global_load_lds_dwordx4 v[208:209], off
	s_add_i32 m0, s19, 0x2000
	v_lshl_add_u64 v[208:209], v[238:239], 0, s[70:71]
	global_load_lds_dwordx4 v[208:209], off
	s_barrier
	s_waitcnt lgkmcnt(0)
	v_mfma_f32_16x16x32_bf16 v[118:121], v[222:225], v[146:149], v[118:121]
	v_mfma_f32_16x16x32_bf16 v[110:113], v[230:233], v[146:149], v[110:113]
	v_mfma_f32_16x16x32_bf16 v[102:105], v[222:225], v[188:191], v[102:105]
	v_mfma_f32_16x16x32_bf16 v[98:101], v[230:233], v[188:191], v[98:101]
	v_mfma_f32_16x16x32_bf16 v[86:89], v[222:225], v[196:199], v[86:89]
	v_mfma_f32_16x16x32_bf16 v[78:81], v[230:233], v[196:199], v[78:81]
	v_mfma_f32_16x16x32_bf16 v[62:65], v[222:225], v[204:207], v[62:65]
	v_mfma_f32_16x16x32_bf16 v[58:61], v[230:233], v[204:207], v[58:61]
	v_mfma_f32_16x16x32_bf16 v[118:121], v[226:229], v[150:153], v[118:121]
	v_mfma_f32_16x16x32_bf16 v[110:113], v[234:237], v[150:153], v[110:113]
	v_mfma_f32_16x16x32_bf16 v[102:105], v[226:229], v[192:195], v[102:105]
	v_mfma_f32_16x16x32_bf16 v[98:101], v[234:237], v[192:195], v[98:101]
	v_mfma_f32_16x16x32_bf16 v[86:89], v[226:229], v[200:203], v[86:89]
	v_mfma_f32_16x16x32_bf16 v[78:81], v[234:237], v[200:203], v[78:81]
	v_mfma_f32_16x16x32_bf16 v[62:65], v[226:229], v[218:221], v[62:65]
	v_mfma_f32_16x16x32_bf16 v[58:61], v[234:237], v[218:221], v[58:61]
	s_mov_b32 m0, s85
	v_lshl_add_u64 v[208:209], v[240:241], 0, s[70:71]
	s_barrier
	ds_read_b128 v[146:149], v216 offset:49152
	ds_read_b128 v[150:153], v216 offset:50176
	ds_read_b128 v[188:191], v216 offset:51200
	ds_read_b128 v[192:195], v216 offset:52224
	ds_read_b128 v[196:199], v216 offset:53248
	ds_read_b128 v[200:203], v216 offset:54272
	ds_read_b128 v[204:207], v216 offset:55296
	ds_read_b128 v[218:221], v216 offset:56320
	global_load_lds_dwordx4 v[208:209], off
	s_mov_b32 m0, s86
	v_lshl_add_u64 v[208:209], v[242:243], 0, s[70:71]
	global_load_lds_dwordx4 v[208:209], off
	s_barrier
	s_waitcnt lgkmcnt(0)
	v_mfma_f32_16x16x32_bf16 v[70:73], v[130:133], v[146:149], v[70:73]
	v_mfma_f32_16x16x32_bf16 v[66:69], v[138:141], v[146:149], v[66:69]
	v_mfma_f32_16x16x32_bf16 v[46:49], v[130:133], v[188:191], v[46:49]
	v_mfma_f32_16x16x32_bf16 v[42:45], v[138:141], v[188:191], v[42:45]
	v_mfma_f32_16x16x32_bf16 v[30:33], v[130:133], v[196:199], v[30:33]
	v_mfma_f32_16x16x32_bf16 v[26:29], v[138:141], v[196:199], v[26:29]
	v_mfma_f32_16x16x32_bf16 v[14:17], v[130:133], v[204:207], v[14:17]
	v_mfma_f32_16x16x32_bf16 v[10:13], v[138:141], v[204:207], v[10:13]
	v_mfma_f32_16x16x32_bf16 v[70:73], v[134:137], v[150:153], v[70:73]
	v_mfma_f32_16x16x32_bf16 v[66:69], v[142:145], v[150:153], v[66:69]
	v_mfma_f32_16x16x32_bf16 v[46:49], v[134:137], v[192:195], v[46:49]
	v_mfma_f32_16x16x32_bf16 v[42:45], v[142:145], v[192:195], v[42:45]
	v_mfma_f32_16x16x32_bf16 v[30:33], v[134:137], v[200:203], v[30:33]
	v_mfma_f32_16x16x32_bf16 v[26:29], v[142:145], v[200:203], v[26:29]
	v_mfma_f32_16x16x32_bf16 v[14:17], v[134:137], v[218:221], v[14:17]
	v_mfma_f32_16x16x32_bf16 v[10:13], v[142:145], v[218:221], v[10:13]
	s_barrier
	s_add_u32 s26, s46, 0x40080
	s_addc_u32 s27, s47, 0
	s_add_i32 s19, s38, s80
	s_mov_b32 m0, s19
	v_lshl_add_u64 v[130:131], s[26:27], 0, v[178:179]
	global_load_lds_dwordx4 v[130:131], off
	s_add_i32 m0, s19, 0x2000
	v_lshl_add_u64 v[130:131], s[26:27], 0, v[182:183]
	global_load_lds_dwordx4 v[130:131], off
	s_waitcnt vmcnt(6)
	s_barrier
	v_mfma_f32_16x16x32_bf16 v[50:53], v[222:225], v[146:149], v[50:53]
	v_mfma_f32_16x16x32_bf16 v[54:57], v[230:233], v[146:149], v[54:57]
	v_mfma_f32_16x16x32_bf16 v[34:37], v[222:225], v[188:191], v[34:37]
	v_mfma_f32_16x16x32_bf16 v[38:41], v[230:233], v[188:191], v[38:41]
	v_mfma_f32_16x16x32_bf16 v[18:21], v[222:225], v[196:199], v[18:21]
	v_mfma_f32_16x16x32_bf16 v[22:25], v[230:233], v[196:199], v[22:25]
	v_mfma_f32_16x16x32_bf16 v[0:3], v[222:225], v[204:207], v[0:3]
	v_mfma_f32_16x16x32_bf16 v[4:7], v[230:233], v[204:207], v[4:7]
	v_mfma_f32_16x16x32_bf16 v[50:53], v[226:229], v[150:153], v[50:53]
	v_mfma_f32_16x16x32_bf16 v[54:57], v[234:237], v[150:153], v[54:57]
	v_mfma_f32_16x16x32_bf16 v[34:37], v[226:229], v[192:195], v[34:37]
	v_mfma_f32_16x16x32_bf16 v[38:41], v[234:237], v[192:195], v[38:41]
	v_mfma_f32_16x16x32_bf16 v[18:21], v[226:229], v[200:203], v[18:21]
	v_mfma_f32_16x16x32_bf16 v[22:25], v[234:237], v[200:203], v[22:25]
	v_mfma_f32_16x16x32_bf16 v[0:3], v[226:229], v[218:221], v[0:3]
	v_mfma_f32_16x16x32_bf16 v[4:7], v[234:237], v[218:221], v[4:7]
	s_add_i32 s18, s18, 2
	s_add_u32 s8, s8, 0x100
	s_addc_u32 s9, s9, 0
	s_add_u32 s13, s13, 0x100
	s_addc_u32 s15, s15, 0
	s_cmp_gt_u32 s18, 13
	s_barrier
	s_cbranch_scc0 .LBB0_276
	s_branch .Lip13l_a_out
; DEVI size_t gemm_offB(const Gemm& g, const Unit& u) { return (g.split ? (size_t)(u.b >> 2) * g.sB + (size_t)(u.b & 3) * g.sB_lo : (size_t)u.b * g.sB) + (size_t)(u.pm >> g.pmsh) * g.sBpm; }
; #define PG8_STAGE(bufoff, gbase, voff) do { _Pragma("unroll") for (int _i = 0; _i < 2; ++_i) \
;         __builtin_amdgcn_global_load_lds((const unsigned*)((const char*)(gbase) + (voff)[_i]), (LAS unsigned*)(lds + (bufoff) + ldsw + _i * 8192), 16, 0, 0); } while (0)
; #define PG8_LDA(dst, b, h) do { _Pragma("unroll") for (int m = 0; m < 4; ++m) _Pragma("unroll") for (int k = 0; k < 2; ++k) dst[m][k] = *(const LAS bf16x8*)(lds + PG8_SA(b, h) + aoff + m * 2048 + k * 1024); } while (0)
; #define PG8_LDB(dst, b, h) do { _Pragma("unroll") for (int n = 0; n < 2; ++n) _Pragma("unroll") for (int k = 0; k < 2; ++k) dst[n][k] = *(const LAS bf16x8*)(lds + PG8_SB(b, h) + boff + n * 2048 + k * 1024); } while (0)
; #define PG8_MMA(ai, bj, At, Bt) do { __builtin_amdgcn_s_setprio(1); _Pragma("unroll") for (int m = 0; m < 4; ++m) _Pragma("unroll") for (int n = 0; n < 2; ++n) _Pragma("unroll") for (int k = 0; k < 2; ++k) \
;         acc[ai][bj][m][n] = __builtin_amdgcn_mfma_f32_16x16x32_bf16(Bt[n][k], At[m][k], acc[ai][bj][m][n], 0, 0, 0); __builtin_amdgcn_s_setprio(0); } while (0)
; #define PG8_WAIT_L(n) asm volatile("s_waitcnt lgkmcnt(" #n ")" ::: "memory")
; #define PG8_BAR __builtin_amdgcn_s_barrier()
; #define PG8_SCHED __builtin_amdgcn_sched_barrier(0)
; template <class Epi>
; DEVI void gemm_phase(LAS unsigned char* lds, const Gemm g, const Epi& E) {
;     ...
;         const bool has_next = unit_next(g, ui + 1, nxt);
;         const char* nA = has_next ? (const char*)g.A + gemm_offA(g, nxt) * 2 + (size_t)nxt.pm * tstepA : cA;
;         const char* nB = has_next ? (const char*)g.Bt + gemm_offB(g, nxt) * 2 + (size_t)nxt.pn * tstepB : cB;
;         for (int t = 0; t < nt; t += 2) {
;             const bool last = (t == nt - 2);
;             const char* a1 = cA + (size_t)(t + 1) * kstep;
;             const char* a2 = last ? nA : cA + (size_t)(t + 2) * kstep; const char* b2 = last ? nB : cB + (size_t)(t + 2) * kstep;
;             const char* a3 = a2 + kstep; const char* b3 = b2 + kstep;
;             PG8_LDB(B0, 0, 0); PG8_SCHED; PG8_LDA(At, 0, 0); PG8_STAGE(PG8_SA(1, 1), a1 + hstepA, voffA);
;             PG8_WAIT_L(8); PG8_BAR; PG8_WAIT_L(0); PG8_MMA(0, 0, At, B0); PG8_BAR; PG8_SCHED;
.Lip13l_a_in:
	s_and_b32 s101, s66, 0xc0
	s_mov_b32 s100, 1
	s_cmp_lg_u32 s101, 0
	s_cselect_b32 s101, 1, 0
	s_add_u32 s19, s8, 0xfffc0080
	s_addc_u32 s26, s9, -1
	s_add_i32 s27, 0, 0x10000
	v_add_u32_e32 v8, s27, v214
	ds_read_b128 v[130:133], v8
	ds_read_b128 v[134:137], v8 offset:1024
	ds_read_b128 v[138:141], v8 offset:2048
	ds_read_b128 v[142:145], v8 offset:3072
	s_cmp_eq_u32 s18, 12
	s_cselect_b32 s69, s0, s26
	s_cselect_b32 s68, s1, s19
	s_cselect_b32 s47, s5, s15
	s_cselect_b32 s46, s7, s13
	v_lshl_add_u64 v[208:209], s[8:9], 0, v[184:185]
	s_add_i32 m0, s81, 0xc000
	ds_read_b128 v[146:149], v216
	ds_read_b128 v[150:153], v216 offset:1024
	ds_read_b128 v[188:191], v216 offset:2048
	ds_read_b128 v[192:195], v216 offset:3072
	ds_read_b128 v[196:199], v216 offset:4096
	ds_read_b128 v[200:203], v216 offset:5120
	ds_read_b128 v[204:207], v216 offset:6144
	ds_read_b128 v[218:221], v216 offset:7168
	global_load_lds_dwordx4 v[208:209], off
	s_add_i32 m0, s81, 0xe000
	v_lshl_add_u64 v[208:209], s[8:9], 0, v[186:187]
	global_load_lds_dwordx4 v[208:209], off
	s_waitcnt lgkmcnt(8)
	s_barrier
	s_waitcnt lgkmcnt(0)
	s_cmp_lg_u32 s101, 0
	s_cbranch_scc1 .Lip13l_a_0
	v_mfma_f32_16x16x32_bf16 v[126:129], v[130:133], v[146:149], 0
	v_mfma_f32_16x16x32_bf16 v[122:125], v[138:141], v[146:149], 0
	v_mfma_f32_16x16x32_bf16 v[114:117], v[130:133], v[188:191], 0
	v_mfma_f32_16x16x32_bf16 v[106:109], v[138:141], v[188:191], 0
	v_mfma_f32_16x16x32_bf16 v[94:97], v[130:133], v[196:199], 0
	v_mfma_f32_16x16x32_bf16 v[90:93], v[138:141], v[196:199], 0
	v_mfma_f32_16x16x32_bf16 v[82:85], v[130:133], v[204:207], 0
	v_mfma_f32_16x16x32_bf16 v[74:77], v[138:141], v[204:207], 0
	v_mfma_f32_16x16x32_bf16 v[126:129], v[134:137], v[150:153], v[126:129]
	v_mfma_f32_16x16x32_bf16 v[122:125], v[142:145], v[150:153], v[122:125]
	v_mfma_f32_16x16x32_bf16 v[114:117], v[134:137], v[192:195], v[114:117]
	v_mfma_f32_16x16x32_bf16 v[106:109], v[142:145], v[192:195], v[106:109]
	v_mfma_f32_16x16x32_bf16 v[94:97], v[134:137], v[200:203], v[94:97]
	v_mfma_f32_16x16x32_bf16 v[90:93], v[142:145], v[200:203], v[90:93]
	v_mfma_f32_16x16x32_bf16 v[82:85], v[134:137], v[218:221], v[82:85]
	v_mfma_f32_16x16x32_bf16 v[74:77], v[142:145], v[218:221], v[74:77]

; template <class Epi>
; DEVI void gemm_phase(LAS unsigned char* lds, const Gemm g, const Epi& E) {
;     ...
;             const int row0 = cur.pm * BM + wr * 64 + fr, col0 = cur.pn * BM + wc * 32 + (Epi::PERM ? 8 : 4) * fq; constexpr int NST = Epi::PERM ? 4 : 16;
;             float rsv[8];
;             if constexpr (Epi::RS) { f32x4 q4[8];
; #pragma unroll
;                 for (int i = 0; i < 8; ++i) q4[i] = *(const f32x4*)(E.ssq_in + (size_t)(row0 + (i >> 2) * HALF + (i & 3) * 16) * 4);
; #pragma unroll
;                 for (int i = 0; i < 8; ++i) rsv[i] = rsqrtf((((q4[i][0] + q4[i][1]) + q4[i][2]) + q4[i][3]) * (1.f / DM) + 1e-6f); }
.Lip13l_a_out:
	s_setprio 0
	v_lshl_add_u32 v204, s6, 8, v213
	v_add_u32_e32 v188, 0xb0, v204
	v_ashrrev_i32_e32 v205, 31, v204
	v_or_b32_e32 v202, 16, v204
	v_ashrrev_i32_e32 v189, 31, v188
	v_lshl_add_u64 v[130:131], v[204:205], 4, s[76:77]
	v_ashrrev_i32_e32 v203, 31, v202
	v_lshl_add_u64 v[134:135], v[188:189], 4, s[76:77]
	global_load_dwordx4 v[206:209], v[130:131], off
	v_or_b32_e32 v200, 32, v204
	global_load_dwordx4 v[134:137], v[134:135], off
	v_lshl_add_u64 v[130:131], v[202:203], 4, s[76:77]
	global_load_dwordx4 v[218:221], v[130:131], off
	v_ashrrev_i32_e32 v201, 31, v200
	v_or_b32_e32 v198, 48, v204
	v_lshl_add_u64 v[130:131], v[200:201], 4, s[76:77]
	v_ashrrev_i32_e32 v199, 31, v198
	v_add_u32_e32 v196, 0x80, v204
	global_load_dwordx4 v[146:149], v[130:131], off
	v_lshl_add_u64 v[130:131], v[198:199], 4, s[76:77]
	v_ashrrev_i32_e32 v197, 31, v196
	v_add_u32_e32 v194, 0x90, v204
	global_load_dwordx4 v[150:153], v[130:131], off
	v_lshl_add_u64 v[130:131], v[196:197], 4, s[76:77]
	v_ashrrev_i32_e32 v195, 31, v194
	v_add_u32_e32 v192, 0xa0, v204
	global_load_dwordx4 v[138:141], v[130:131], off
	v_lshl_add_u64 v[130:131], v[194:195], 4, s[76:77]
	v_ashrrev_i32_e32 v193, 31, v192
	global_load_dwordx4 v[142:145], v[130:131], off
	v_lshl_add_u64 v[130:131], v[192:193], 4, s[76:77]
	global_load_dwordx4 v[130:133], v[130:131], off
	s_waitcnt vmcnt(0)
	v_mov_b32_e32 v191, v206
	v_mov_b32_e32 v190, v218
	v_mov_b32_e32 v206, v219
	v_pk_add_f32 v[190:191], v[190:191], v[206:207]
	v_mov_b32_e32 v206, v220
	v_mov_b32_e32 v207, v208
	v_pk_add_f32 v[190:191], v[206:207], v[190:191]
	v_mov_b32_e32 v208, v221
	v_pk_add_f32 v[190:191], v[208:209], v[190:191]
	s_nop 0
	v_pk_fma_f32 v[206:207], v[190:191], s[72:73], v[160:161] op_sel_hi:[1,0,0]
	v_lshl_or_b32 v190, s4, 8, v215
	v_mul_f32_e32 v8, 0x4b800000, v207
	v_cmp_gt_f32_e32 vcc, s94, v207
	v_cmp_gt_f32_e64 s[6:7], s94, v206
	s_nop 0
	v_cndmask_b32_e32 v8, v207, v8, vcc
	v_rsq_f32_e32 v8, v8
	s_nop 0
	v_mul_f32_e32 v162, 0x45800000, v8
	v_cndmask_b32_e32 v208, v8, v162, vcc
	v_pk_mul_f32 v[128:129], v[128:129], v[208:209] op_sel_hi:[1,0]
	v_pk_mul_f32 v[126:127], v[126:127], v[208:209] op_sel_hi:[1,0]
	v_pk_mul_f32 v[124:125], v[124:125], v[208:209] op_sel_hi:[1,0]
	v_pk_mul_f32 v[122:123], v[122:123], v[208:209] op_sel_hi:[1,0]
	v_cmp_lt_i32_e32 vcc, s39, v190
	v_add_u32_e32 v8, 0xfffff400, v190
	s_and_saveexec_b64 s[0:1], vcc
	s_xor_b64 s[8:9], exec, s[0:1]
	s_cbranch_execz .LBB0_281
	v_cmp_gt_u32_e64 s[4:5], 16, v8
	s_and_saveexec_b64 s[46:47], s[4:5]
	s_cbranch_execz .LBB0_280
	v_lshlrev_b64 v[218:219], 6, v[204:205]
	v_lshl_add_u64 v[218:219], s[58:59], 0, v[218:219]
	v_lshl_add_u64 v[218:219], v[8:9], 2, v[218:219]
	global_store_dwordx4 v[218:219], v[126:129], off
	global_store_dwordx4 v[218:219], v[122:125], off offset:16

; #define PG8_STAGE(bufoff, gbase, voff) do { _Pragma("unroll") for (int _i = 0; _i < 2; ++_i) \
;         __builtin_amdgcn_global_load_lds((const unsigned*)((const char*)(gbase) + (voff)[_i]), (LAS unsigned*)(lds + (bufoff) + ldsw + _i * 8192), 16, 0, 0); } while (0)
; #define PG8_LDA(dst, b, h) do { _Pragma("unroll") for (int m = 0; m < 4; ++m) _Pragma("unroll") for (int k = 0; k < 2; ++k) dst[m][k] = *(const LAS bf16x8*)(lds + PG8_SA(b, h) + aoff + m * 2048 + k * 1024); } while (0)
; #define PG8_LDB(dst, b, h) do { _Pragma("unroll") for (int n = 0; n < 2; ++n) _Pragma("unroll") for (int k = 0; k < 2; ++k) dst[n][k] = *(const LAS bf16x8*)(lds + PG8_SB(b, h) + boff + n * 2048 + k * 1024); } while (0)
; #define PG8_MMA(ai, bj, At, Bt) do { __builtin_amdgcn_s_setprio(1); _Pragma("unroll") for (int m = 0; m < 4; ++m) _Pragma("unroll") for (int n = 0; n < 2; ++n) _Pragma("unroll") for (int k = 0; k < 2; ++k) \
;         acc[ai][bj][m][n] = __builtin_amdgcn_mfma_f32_16x16x32_bf16(Bt[n][k], At[m][k], acc[ai][bj][m][n], 0, 0, 0); __builtin_amdgcn_s_setprio(0); } while (0)
; #define PG8_WAIT_L(n) asm volatile("s_waitcnt lgkmcnt(" #n ")" ::: "memory")
; #define PG8_BAR __builtin_amdgcn_s_barrier()
; #define PG8_SCHED __builtin_amdgcn_sched_barrier(0)
; template <class Epi>
; DEVI void gemm_phase(LAS unsigned char* lds, const Gemm g, const Epi& E) {
;     ...
;         for (int t = 0; t < nt; t += 2) {
;             const bool last = (t == nt - 2);
;             const char* a1 = cA + (size_t)(t + 1) * kstep;
;             const char* a2 = last ? nA : cA + (size_t)(t + 2) * kstep; const char* b2 = last ? nB : cB + (size_t)(t + 2) * kstep;
;             const char* a3 = a2 + kstep; const char* b3 = b2 + kstep;
;             PG8_LDB(B0, 0, 0); PG8_SCHED; PG8_LDA(At, 0, 0); PG8_STAGE(PG8_SA(1, 1), a1 + hstepA, voffA);
;             PG8_WAIT_L(8); PG8_BAR; PG8_WAIT_L(0); PG8_MMA(0, 0, At, B0); PG8_BAR; PG8_SCHED;
;             PG8_LDB(B1, 0, 1); PG8_STAGE(PG8_SB(0, 0), b2, voffB);
;             PG8_BAR; PG8_WAIT_L(0); PG8_MMA(0, 1, At, B1); PG8_BAR;
;             PG8_LDA(At, 0, 1); PG8_STAGE(PG8_SA(0, 0), a2, voffA);
;             PG8_BAR; PG8_WAIT_L(0); PG8_MMA(1, 0, At, B0); PG8_BAR; PG8_SCHED;
.LBB0_355:
	s_ashr_i32 s11, s10, 31
	v_mov_b64_e32 v[0:1], 0x680
	s_lshl_b64 s[0:1], s[10:11], 19
	v_cmp_lt_i64_e32 vcc, s[14:15], v[0:1]
	s_add_u32 s14, s24, s0
	s_addc_u32 s15, s25, s1
	s_and_b64 s[0:1], vcc, exec
	s_cselect_b32 s0, s15, s9
	s_cselect_b32 s1, s14, s8
	s_ashr_i32 s13, s12, 31
	s_lshl_b64 s[16:17], s[12:13], 19
	s_add_u32 s16, s82, s16
	s_addc_u32 s17, s83, s17
	s_and_b64 s[18:19], vcc, exec
	s_cselect_b32 s5, s17, s47
	s_cselect_b32 s7, s16, s46
	s_add_u32 s8, s8, 0x40080
	s_addc_u32 s9, s9, 0
	s_add_u32 s11, s46, 0x100
	s_addc_u32 s13, s47, 0
	s_mov_b32 s18, -2
	s_cmp_eq_u32 s4, 12
	s_cbranch_scc1 .Lip13l_b_in
	s_add_u32 s19, s8, 0xfffc0080
	s_addc_u32 s26, s9, -1
	s_add_i32 s27, 0, 0x10000
	v_add_u32_e32 v142, s27, v209
	ds_read_b128 v[130:133], v142
	ds_read_b128 v[134:137], v142 offset:1024
	ds_read_b128 v[138:141], v142 offset:2048
	ds_read_b128 v[142:145], v142 offset:3072
	s_cmp_eq_u32 s18, 12
	s_cselect_b32 s69, s0, s26
	s_cselect_b32 s68, s1, s19
	s_cselect_b32 s47, s5, s13
	s_cselect_b32 s46, s7, s11
	v_lshl_add_u64 v[206:207], s[8:9], 0, v[182:183]
	s_add_i32 m0, s85, 0xc000
	ds_read_b128 v[146:149], v214
	ds_read_b128 v[150:153], v214 offset:1024
	ds_read_b128 v[186:189], v214 offset:2048
	ds_read_b128 v[190:193], v214 offset:3072
	ds_read_b128 v[194:197], v214 offset:4096
	ds_read_b128 v[198:201], v214 offset:5120
	ds_read_b128 v[202:205], v214 offset:6144
	ds_read_b128 v[216:219], v214 offset:7168
	global_load_lds_dwordx4 v[206:207], off
	s_add_i32 m0, s85, 0xe000
	v_lshl_add_u64 v[206:207], s[8:9], 0, v[184:185]
	global_load_lds_dwordx4 v[206:207], off
	s_waitcnt lgkmcnt(8)
	s_barrier
	s_waitcnt lgkmcnt(0)
	v_mfma_f32_16x16x32_bf16 v[126:129], v[130:133], v[146:149], 0
	v_mfma_f32_16x16x32_bf16 v[122:125], v[138:141], v[146:149], 0
	v_mfma_f32_16x16x32_bf16 v[114:117], v[130:133], v[186:189], 0
	v_mfma_f32_16x16x32_bf16 v[106:109], v[138:141], v[186:189], 0
	v_mfma_f32_16x16x32_bf16 v[94:97], v[130:133], v[194:197], 0
	v_mfma_f32_16x16x32_bf16 v[90:93], v[138:141], v[194:197], 0
	v_mfma_f32_16x16x32_bf16 v[82:85], v[130:133], v[202:205], 0
	v_mfma_f32_16x16x32_bf16 v[74:77], v[138:141], v[202:205], 0
	v_mfma_f32_16x16x32_bf16 v[126:129], v[134:137], v[150:153], v[126:129]
	v_mfma_f32_16x16x32_bf16 v[122:125], v[142:145], v[150:153], v[122:125]
	v_mfma_f32_16x16x32_bf16 v[114:117], v[134:137], v[190:193], v[114:117]
	v_mfma_f32_16x16x32_bf16 v[106:109], v[142:145], v[190:193], v[106:109]
	v_mfma_f32_16x16x32_bf16 v[94:97], v[134:137], v[198:201], v[94:97]
	v_mfma_f32_16x16x32_bf16 v[90:93], v[142:145], v[198:201], v[90:93]
	v_mfma_f32_16x16x32_bf16 v[82:85], v[134:137], v[216:219], v[82:85]
	v_mfma_f32_16x16x32_bf16 v[74:77], v[142:145], v[216:219], v[74:77]
	s_barrier
	s_add_i32 s19, 0, 0x14000
	s_add_i32 s26, s27, s84
	v_add_u32_e32 v162, s19, v209
	v_lshl_add_u64 v[206:207], s[46:47], 0, v[8:9]
	s_mov_b32 m0, s26
	ds_read_b128 v[220:223], v162
	ds_read_b128 v[224:227], v162 offset:1024
	ds_read_b128 v[228:231], v162 offset:2048
	ds_read_b128 v[232:235], v162 offset:3072
	global_load_lds_dwordx4 v[206:207], off
	s_add_i32 m0, s26, 0x2000
	v_lshl_add_u64 v[236:237], s[46:47], 0, v[180:181]
	global_load_lds_dwordx4 v[236:237], off
	s_barrier
	s_waitcnt lgkmcnt(0)
	v_mfma_f32_16x16x32_bf16 v[118:121], v[220:223], v[146:149], 0
	v_mfma_f32_16x16x32_bf16 v[110:113], v[228:231], v[146:149], 0
	v_mfma_f32_16x16x32_bf16 v[102:105], v[220:223], v[186:189], 0
	v_mfma_f32_16x16x32_bf16 v[98:101], v[228:231], v[186:189], 0
	v_mfma_f32_16x16x32_bf16 v[86:89], v[220:223], v[194:197], 0
	v_mfma_f32_16x16x32_bf16 v[78:81], v[228:231], v[194:197], 0
	v_mfma_f32_16x16x32_bf16 v[62:65], v[220:223], v[202:205], 0
	v_mfma_f32_16x16x32_bf16 v[58:61], v[228:231], v[202:205], 0
	v_mfma_f32_16x16x32_bf16 v[118:121], v[224:227], v[150:153], v[118:121]
	v_mfma_f32_16x16x32_bf16 v[110:113], v[232:235], v[150:153], v[110:113]
	v_mfma_f32_16x16x32_bf16 v[102:105], v[224:227], v[190:193], v[102:105]
	v_mfma_f32_16x16x32_bf16 v[98:101], v[232:235], v[190:193], v[98:101]
	v_mfma_f32_16x16x32_bf16 v[86:89], v[224:227], v[198:201], v[86:89]
	v_mfma_f32_16x16x32_bf16 v[78:81], v[232:235], v[198:201], v[78:81]
	v_mfma_f32_16x16x32_bf16 v[62:65], v[224:227], v[216:219], v[62:65]
	v_mfma_f32_16x16x32_bf16 v[58:61], v[232:235], v[216:219], v[58:61]
	s_mov_b32 m0, s85
	v_lshl_add_u64 v[238:239], s[68:69], 0, v[176:177]
	s_barrier
	ds_read_b128 v[146:149], v214 offset:16384
	ds_read_b128 v[150:153], v214 offset:17408
	ds_read_b128 v[186:189], v214 offset:18432
	ds_read_b128 v[190:193], v214 offset:19456
	ds_read_b128 v[194:197], v214 offset:20480
	ds_read_b128 v[198:201], v214 offset:21504
	ds_read_b128 v[202:205], v214 offset:22528
	ds_read_b128 v[216:219], v214 offset:23552
	global_load_lds_dwordx4 v[238:239], off
	s_mov_b32 m0, s86
	v_lshl_add_u64 v[240:241], s[68:69], 0, v[178:179]
	global_load_lds_dwordx4 v[240:241], off
	s_barrier
	s_waitcnt lgkmcnt(0)
	v_mfma_f32_16x16x32_bf16 v[70:73], v[130:133], v[146:149], 0
	v_mfma_f32_16x16x32_bf16 v[66:69], v[138:141], v[146:149], 0
	v_mfma_f32_16x16x32_bf16 v[46:49], v[130:133], v[186:189], 0
	v_mfma_f32_16x16x32_bf16 v[42:45], v[138:141], v[186:189], 0
	v_mfma_f32_16x16x32_bf16 v[30:33], v[130:133], v[194:197], 0
	v_mfma_f32_16x16x32_bf16 v[26:29], v[138:141], v[194:197], 0
	v_mfma_f32_16x16x32_bf16 v[14:17], v[130:133], v[202:205], 0
	v_mfma_f32_16x16x32_bf16 v[10:13], v[138:141], v[202:205], 0
	v_mfma_f32_16x16x32_bf16 v[70:73], v[134:137], v[150:153], v[70:73]
	v_mfma_f32_16x16x32_bf16 v[66:69], v[142:145], v[150:153], v[66:69]
	v_mfma_f32_16x16x32_bf16 v[46:49], v[134:137], v[190:193], v[46:49]
	v_mfma_f32_16x16x32_bf16 v[42:45], v[142:145], v[190:193], v[42:45]
	v_mfma_f32_16x16x32_bf16 v[30:33], v[134:137], v[198:201], v[30:33]
	v_mfma_f32_16x16x32_bf16 v[26:29], v[142:145], v[198:201], v[26:29]
	v_mfma_f32_16x16x32_bf16 v[14:17], v[134:137], v[216:219], v[14:17]
	v_mfma_f32_16x16x32_bf16 v[10:13], v[142:145], v[216:219], v[10:13]
	s_barrier
; #define PG8_STAGE(bufoff, gbase, voff) do { _Pragma("unroll") for (int _i = 0; _i < 2; ++_i) \
;         __builtin_amdgcn_global_load_lds((const unsigned*)((const char*)(gbase) + (voff)[_i]), (LAS unsigned*)(lds + (bufoff) + ldsw + _i * 8192), 16, 0, 0); } while (0)
; #define PG8_LDA(dst, b, h) do { _Pragma("unroll") for (int m = 0; m < 4; ++m) _Pragma("unroll") for (int k = 0; k < 2; ++k) dst[m][k] = *(const LAS bf16x8*)(lds + PG8_SA(b, h) + aoff + m * 2048 + k * 1024); } while (0)
; #define PG8_LDB(dst, b, h) do { _Pragma("unroll") for (int n = 0; n < 2; ++n) _Pragma("unroll") for (int k = 0; k < 2; ++k) dst[n][k] = *(const LAS bf16x8*)(lds + PG8_SB(b, h) + boff + n * 2048 + k * 1024); } while (0)
; #define PG8_MMA(ai, bj, At, Bt) do { __builtin_amdgcn_s_setprio(1); _Pragma("unroll") for (int m = 0; m < 4; ++m) _Pragma("unroll") for (int n = 0; n < 2; ++n) _Pragma("unroll") for (int k = 0; k < 2; ++k) \
;         acc[ai][bj][m][n] = __builtin_amdgcn_mfma_f32_16x16x32_bf16(Bt[n][k], At[m][k], acc[ai][bj][m][n], 0, 0, 0); __builtin_amdgcn_s_setprio(0); } while (0)
; #define PG8_WAIT_V(n) asm volatile("s_waitcnt vmcnt(" #n ")" ::: "memory")
; #define PG8_WAIT_L(n) asm volatile("s_waitcnt lgkmcnt(" #n ")" ::: "memory")
; #define PG8_BAR __builtin_amdgcn_s_barrier()
; #define PG8_SCHED __builtin_amdgcn_sched_barrier(0)
; template <class Epi>
; DEVI void gemm_phase(LAS unsigned char* lds, const Gemm g, const Epi& E) {
;     ...
;             PG8_BAR; PG8_WAIT_L(0); PG8_MMA(1, 0, At, B0); PG8_BAR; PG8_SCHED;
;             PG8_STAGE(PG8_SB(0, 1), b2 + hstepB, voffB);
;             PG8_WAIT_V(6); PG8_BAR; PG8_MMA(1, 1, At, B1); PG8_BAR;
;             PG8_LDB(B0, 1, 0); PG8_SCHED; PG8_LDA(At, 1, 0); PG8_STAGE(PG8_SA(0, 1), a2 + hstepA, voffA);
;             PG8_WAIT_L(8); PG8_BAR; PG8_WAIT_L(0); PG8_MMA(0, 0, At, B0); PG8_BAR; PG8_SCHED;
;             PG8_LDB(B1, 1, 1); PG8_STAGE(PG8_SB(1, 0), b3, voffB);
;             PG8_BAR; PG8_WAIT_L(0); PG8_MMA(0, 1, At, B1); PG8_BAR;
;             PG8_LDA(At, 1, 1); PG8_STAGE(PG8_SA(1, 0), a3, voffA);
;             PG8_BAR; PG8_WAIT_L(0); PG8_MMA(1, 0, At, B0); PG8_BAR; PG8_SCHED;
;             PG8_STAGE(PG8_SB(1, 1), b3 + hstepB, voffB);
;             PG8_WAIT_V(6); PG8_BAR; PG8_MMA(1, 1, At, B1); PG8_BAR;
	s_add_u32 s26, s46, 0x40000
	s_addc_u32 s27, s47, 0
	s_add_i32 s19, s19, s84
	s_mov_b32 m0, s19
	v_lshl_add_u64 v[130:131], s[26:27], 0, v[8:9]
	global_load_lds_dwordx4 v[130:131], off
	s_add_i32 m0, s19, 0x2000
	v_lshl_add_u64 v[130:131], s[26:27], 0, v[180:181]
	global_load_lds_dwordx4 v[130:131], off
	s_waitcnt vmcnt(6)
	s_barrier
	v_mfma_f32_16x16x32_bf16 v[50:53], v[220:223], v[146:149], 0
	v_mfma_f32_16x16x32_bf16 v[54:57], v[228:231], v[146:149], 0
	v_mfma_f32_16x16x32_bf16 v[34:37], v[220:223], v[186:189], 0
	v_mfma_f32_16x16x32_bf16 v[38:41], v[228:231], v[186:189], 0
	v_mfma_f32_16x16x32_bf16 v[18:21], v[220:223], v[194:197], 0
	v_mfma_f32_16x16x32_bf16 v[22:25], v[228:231], v[194:197], 0
	v_mfma_f32_16x16x32_bf16 v[0:3], v[220:223], v[202:205], 0
	v_mfma_f32_16x16x32_bf16 v[4:7], v[228:231], v[202:205], 0
	v_mfma_f32_16x16x32_bf16 v[50:53], v[224:227], v[150:153], v[50:53]
	v_mfma_f32_16x16x32_bf16 v[54:57], v[232:235], v[150:153], v[54:57]
	v_mfma_f32_16x16x32_bf16 v[34:37], v[224:227], v[190:193], v[34:37]
	v_mfma_f32_16x16x32_bf16 v[38:41], v[232:235], v[190:193], v[38:41]
	v_mfma_f32_16x16x32_bf16 v[18:21], v[224:227], v[198:201], v[18:21]
	v_mfma_f32_16x16x32_bf16 v[22:25], v[232:235], v[198:201], v[22:25]
	v_mfma_f32_16x16x32_bf16 v[0:3], v[224:227], v[216:219], v[0:3]
	v_mfma_f32_16x16x32_bf16 v[4:7], v[232:235], v[216:219], v[4:7]
	s_add_i32 s19, 0, 0x18000
	v_add_u32_e32 v142, s19, v209
	s_barrier
	ds_read_b128 v[130:133], v142
	ds_read_b128 v[134:137], v142 offset:1024
	ds_read_b128 v[138:141], v142 offset:2048
	ds_read_b128 v[142:145], v142 offset:3072
	s_add_u32 s26, s68, 0x40000
	s_addc_u32 s27, s69, 0
	s_mov_b32 m0, s87
	v_lshl_add_u64 v[220:221], s[26:27], 0, v[176:177]
	ds_read_b128 v[146:149], v214 offset:32768
	ds_read_b128 v[150:153], v214 offset:33792
	ds_read_b128 v[186:189], v214 offset:34816
	ds_read_b128 v[190:193], v214 offset:35840
	ds_read_b128 v[194:197], v214 offset:36864
	ds_read_b128 v[198:201], v214 offset:37888
	ds_read_b128 v[202:205], v214 offset:38912
	ds_read_b128 v[216:219], v214 offset:39936
	global_load_lds_dwordx4 v[220:221], off
	s_mov_b32 m0, s88
	v_lshl_add_u64 v[220:221], s[26:27], 0, v[178:179]
	global_load_lds_dwordx4 v[220:221], off
	s_waitcnt lgkmcnt(8)
	s_barrier
	s_waitcnt lgkmcnt(0)
	v_mfma_f32_16x16x32_bf16 v[126:129], v[130:133], v[146:149], v[126:129]
	v_mfma_f32_16x16x32_bf16 v[122:125], v[138:141], v[146:149], v[122:125]
	v_mfma_f32_16x16x32_bf16 v[114:117], v[130:133], v[186:189], v[114:117]
	v_mfma_f32_16x16x32_bf16 v[106:109], v[138:141], v[186:189], v[106:109]
	v_mfma_f32_16x16x32_bf16 v[94:97], v[130:133], v[194:197], v[94:97]
	v_mfma_f32_16x16x32_bf16 v[90:93], v[138:141], v[194:197], v[90:93]
	v_mfma_f32_16x16x32_bf16 v[82:85], v[130:133], v[202:205], v[82:85]
	v_mfma_f32_16x16x32_bf16 v[74:77], v[138:141], v[202:205], v[74:77]
	v_mfma_f32_16x16x32_bf16 v[126:129], v[134:137], v[150:153], v[126:129]
	v_mfma_f32_16x16x32_bf16 v[122:125], v[142:145], v[150:153], v[122:125]
	v_mfma_f32_16x16x32_bf16 v[114:117], v[134:137], v[190:193], v[114:117]
	v_mfma_f32_16x16x32_bf16 v[106:109], v[142:145], v[190:193], v[106:109]
	v_mfma_f32_16x16x32_bf16 v[94:97], v[134:137], v[198:201], v[94:97]
	v_mfma_f32_16x16x32_bf16 v[90:93], v[142:145], v[198:201], v[90:93]
	v_mfma_f32_16x16x32_bf16 v[82:85], v[134:137], v[216:219], v[82:85]
	v_mfma_f32_16x16x32_bf16 v[74:77], v[142:145], v[216:219], v[74:77]
	s_barrier
	s_add_i32 s38, 0, 0x1c000
	s_add_i32 s19, s19, s84
	v_add_u32_e32 v162, s38, v209
	v_lshl_add_u64 v[206:207], v[206:207], 0, s[70:71]
	s_mov_b32 m0, s19
	ds_read_b128 v[220:223], v162
	ds_read_b128 v[224:227], v162 offset:1024
	ds_read_b128 v[228:231], v162 offset:2048
	ds_read_b128 v[232:235], v162 offset:3072
	global_load_lds_dwordx4 v[206:207], off
	s_add_i32 m0, s19, 0x2000
	v_lshl_add_u64 v[206:207], v[236:237], 0, s[70:71]
	global_load_lds_dwordx4 v[206:207], off
	s_barrier
	s_waitcnt lgkmcnt(0)
	v_mfma_f32_16x16x32_bf16 v[118:121], v[220:223], v[146:149], v[118:121]
	v_mfma_f32_16x16x32_bf16 v[110:113], v[228:231], v[146:149], v[110:113]
	v_mfma_f32_16x16x32_bf16 v[102:105], v[220:223], v[186:189], v[102:105]
	v_mfma_f32_16x16x32_bf16 v[98:101], v[228:231], v[186:189], v[98:101]
	v_mfma_f32_16x16x32_bf16 v[86:89], v[220:223], v[194:197], v[86:89]
	v_mfma_f32_16x16x32_bf16 v[78:81], v[228:231], v[194:197], v[78:81]
	v_mfma_f32_16x16x32_bf16 v[62:65], v[220:223], v[202:205], v[62:65]
	v_mfma_f32_16x16x32_bf16 v[58:61], v[228:231], v[202:205], v[58:61]
	v_mfma_f32_16x16x32_bf16 v[118:121], v[224:227], v[150:153], v[118:121]
	v_mfma_f32_16x16x32_bf16 v[110:113], v[232:235], v[150:153], v[110:113]
	v_mfma_f32_16x16x32_bf16 v[102:105], v[224:227], v[190:193], v[102:105]
	v_mfma_f32_16x16x32_bf16 v[98:101], v[232:235], v[190:193], v[98:101]
	v_mfma_f32_16x16x32_bf16 v[86:89], v[224:227], v[198:201], v[86:89]
	v_mfma_f32_16x16x32_bf16 v[78:81], v[232:235], v[198:201], v[78:81]
	v_mfma_f32_16x16x32_bf16 v[62:65], v[224:227], v[216:219], v[62:65]
	v_mfma_f32_16x16x32_bf16 v[58:61], v[232:235], v[216:219], v[58:61]
	s_mov_b32 m0, s89
	v_lshl_add_u64 v[206:207], v[238:239], 0, s[70:71]
	s_barrier
	ds_read_b128 v[146:149], v214 offset:49152
	ds_read_b128 v[150:153], v214 offset:50176
	ds_read_b128 v[186:189], v214 offset:51200
	ds_read_b128 v[190:193], v214 offset:52224
	ds_read_b128 v[194:197], v214 offset:53248
	ds_read_b128 v[198:201], v214 offset:54272
	ds_read_b128 v[202:205], v214 offset:55296
	ds_read_b128 v[216:219], v214 offset:56320
	global_load_lds_dwordx4 v[206:207], off
	s_mov_b32 m0, s90
	v_lshl_add_u64 v[206:207], v[240:241], 0, s[70:71]
	global_load_lds_dwordx4 v[206:207], off
	s_barrier
; #define PG8_STAGE(bufoff, gbase, voff) do { _Pragma("unroll") for (int _i = 0; _i < 2; ++_i) \
;         __builtin_amdgcn_global_load_lds((const unsigned*)((const char*)(gbase) + (voff)[_i]), (LAS unsigned*)(lds + (bufoff) + ldsw + _i * 8192), 16, 0, 0); } while (0)
; #define PG8_LDA(dst, b, h) do { _Pragma("unroll") for (int m = 0; m < 4; ++m) _Pragma("unroll") for (int k = 0; k < 2; ++k) dst[m][k] = *(const LAS bf16x8*)(lds + PG8_SA(b, h) + aoff + m * 2048 + k * 1024); } while (0)
; #define PG8_LDB(dst, b, h) do { _Pragma("unroll") for (int n = 0; n < 2; ++n) _Pragma("unroll") for (int k = 0; k < 2; ++k) dst[n][k] = *(const LAS bf16x8*)(lds + PG8_SB(b, h) + boff + n * 2048 + k * 1024); } while (0)
; #define PG8_WAIT_V(n) asm volatile("s_waitcnt vmcnt(" #n ")" ::: "memory")
; #define PG8_WAIT_L(n) asm volatile("s_waitcnt lgkmcnt(" #n ")" ::: "memory")
; #define PG8_BAR __builtin_amdgcn_s_barrier()
; #define PG8_SCHED __builtin_amdgcn_sched_barrier(0)
; template <class Epi>
; DEVI void gemm_phase(LAS unsigned char* lds, const Gemm g, const Epi& E) {
;     ...
;             PG8_LDB(B0, 0, 0); PG8_SCHED; PG8_LDA(At, 0, 0); PG8_STAGE(PG8_SA(1, 1), a1 + hstepA, voffA);
;             PG8_WAIT_L(8); PG8_BAR; PG8_WAIT_L(0); PG8_MMA(0, 0, At, B0); PG8_BAR; PG8_SCHED;
;             PG8_LDB(B1, 0, 1); PG8_STAGE(PG8_SB(0, 0), b2, voffB);
;             PG8_BAR; PG8_WAIT_L(0); PG8_MMA(0, 1, At, B1); PG8_BAR;
;             PG8_LDA(At, 0, 1); PG8_STAGE(PG8_SA(0, 0), a2, voffA);
;             PG8_BAR; PG8_WAIT_L(0); PG8_MMA(1, 0, At, B0); PG8_BAR; PG8_SCHED;
;             PG8_STAGE(PG8_SB(0, 1), b2 + hstepB, voffB);
;             PG8_WAIT_V(6); PG8_BAR; PG8_MMA(1, 1, At, B1); PG8_BAR;
;             PG8_LDB(B0, 1, 0); PG8_SCHED; PG8_LDA(At, 1, 0); PG8_STAGE(PG8_SA(0, 1), a2 + hstepA, voffA);
;             PG8_WAIT_L(8); PG8_BAR; PG8_WAIT_L(0); PG8_MMA(0, 0, At, B0); PG8_BAR; PG8_SCHED;
;             PG8_LDB(B1, 1, 1); PG8_STAGE(PG8_SB(1, 0), b3, voffB);
;             PG8_BAR; PG8_WAIT_L(0); PG8_MMA(0, 1, At, B1); PG8_BAR;
;             PG8_LDA(At, 1, 1); PG8_STAGE(PG8_SA(1, 0), a3, voffA);
;             PG8_BAR; PG8_WAIT_L(0); PG8_MMA(1, 0, At, B0); PG8_BAR; PG8_SCHED;
;             PG8_STAGE(PG8_SB(1, 1), b3 + hstepB, voffB);
;             PG8_WAIT_V(6); PG8_BAR; PG8_MMA(1, 1, At, B1); PG8_BAR;
	s_waitcnt lgkmcnt(0)
	v_mfma_f32_16x16x32_bf16 v[70:73], v[130:133], v[146:149], v[70:73]
	v_mfma_f32_16x16x32_bf16 v[66:69], v[138:141], v[146:149], v[66:69]
	v_mfma_f32_16x16x32_bf16 v[46:49], v[130:133], v[186:189], v[46:49]
	v_mfma_f32_16x16x32_bf16 v[42:45], v[138:141], v[186:189], v[42:45]
	v_mfma_f32_16x16x32_bf16 v[30:33], v[130:133], v[194:197], v[30:33]
	v_mfma_f32_16x16x32_bf16 v[26:29], v[138:141], v[194:197], v[26:29]
	v_mfma_f32_16x16x32_bf16 v[14:17], v[130:133], v[202:205], v[14:17]
	v_mfma_f32_16x16x32_bf16 v[10:13], v[138:141], v[202:205], v[10:13]
	v_mfma_f32_16x16x32_bf16 v[70:73], v[134:137], v[150:153], v[70:73]
	v_mfma_f32_16x16x32_bf16 v[66:69], v[142:145], v[150:153], v[66:69]
	v_mfma_f32_16x16x32_bf16 v[46:49], v[134:137], v[190:193], v[46:49]
	v_mfma_f32_16x16x32_bf16 v[42:45], v[142:145], v[190:193], v[42:45]
	v_mfma_f32_16x16x32_bf16 v[30:33], v[134:137], v[198:201], v[30:33]
	v_mfma_f32_16x16x32_bf16 v[26:29], v[142:145], v[198:201], v[26:29]
	v_mfma_f32_16x16x32_bf16 v[14:17], v[134:137], v[216:219], v[14:17]
	v_mfma_f32_16x16x32_bf16 v[10:13], v[142:145], v[216:219], v[10:13]
	s_barrier
	s_add_u32 s26, s46, 0x40080
	s_addc_u32 s27, s47, 0
	s_add_i32 s19, s38, s84
	s_mov_b32 m0, s19
	v_lshl_add_u64 v[130:131], s[26:27], 0, v[8:9]
	global_load_lds_dwordx4 v[130:131], off
	s_add_i32 m0, s19, 0x2000
	v_lshl_add_u64 v[130:131], s[26:27], 0, v[180:181]
	global_load_lds_dwordx4 v[130:131], off
	s_waitcnt vmcnt(6)
	s_barrier
	v_mfma_f32_16x16x32_bf16 v[50:53], v[220:223], v[146:149], v[50:53]
	v_mfma_f32_16x16x32_bf16 v[54:57], v[228:231], v[146:149], v[54:57]
	v_mfma_f32_16x16x32_bf16 v[34:37], v[220:223], v[186:189], v[34:37]
	v_mfma_f32_16x16x32_bf16 v[38:41], v[228:231], v[186:189], v[38:41]
	v_mfma_f32_16x16x32_bf16 v[18:21], v[220:223], v[194:197], v[18:21]
	v_mfma_f32_16x16x32_bf16 v[22:25], v[228:231], v[194:197], v[22:25]
	v_mfma_f32_16x16x32_bf16 v[0:3], v[220:223], v[202:205], v[0:3]
	v_mfma_f32_16x16x32_bf16 v[4:7], v[228:231], v[202:205], v[4:7]
	v_mfma_f32_16x16x32_bf16 v[50:53], v[224:227], v[150:153], v[50:53]
	v_mfma_f32_16x16x32_bf16 v[54:57], v[232:235], v[150:153], v[54:57]
	v_mfma_f32_16x16x32_bf16 v[34:37], v[224:227], v[190:193], v[34:37]
	v_mfma_f32_16x16x32_bf16 v[38:41], v[232:235], v[190:193], v[38:41]
	v_mfma_f32_16x16x32_bf16 v[18:21], v[224:227], v[198:201], v[18:21]
	v_mfma_f32_16x16x32_bf16 v[22:25], v[232:235], v[198:201], v[22:25]
	v_mfma_f32_16x16x32_bf16 v[0:3], v[224:227], v[216:219], v[0:3]
	v_mfma_f32_16x16x32_bf16 v[4:7], v[232:235], v[216:219], v[4:7]
	s_add_i32 s18, s18, 2
	s_add_u32 s8, s8, 0x100
	s_addc_u32 s9, s9, 0
	s_add_u32 s11, s11, 0x100
	s_addc_u32 s13, s13, 0
	s_cmp_gt_u32 s18, 13
	s_barrier
.LBB0_356:
	s_add_u32 s19, s8, 0xfffc0080
	s_addc_u32 s26, s9, -1
	s_add_i32 s27, 0, 0x10000
	v_add_u32_e32 v142, s27, v209
	ds_read_b128 v[130:133], v142
	ds_read_b128 v[134:137], v142 offset:1024
	ds_read_b128 v[138:141], v142 offset:2048
	ds_read_b128 v[142:145], v142 offset:3072
	s_cmp_eq_u32 s18, 12
	s_cselect_b32 s69, s0, s26
	s_cselect_b32 s68, s1, s19
	s_cselect_b32 s47, s5, s13
	s_cselect_b32 s46, s7, s11
	v_lshl_add_u64 v[206:207], s[8:9], 0, v[182:183]
	s_add_i32 m0, s85, 0xc000
	ds_read_b128 v[146:149], v214
	ds_read_b128 v[150:153], v214 offset:1024
	ds_read_b128 v[186:189], v214 offset:2048
	ds_read_b128 v[190:193], v214 offset:3072
	ds_read_b128 v[194:197], v214 offset:4096
	ds_read_b128 v[198:201], v214 offset:5120
	ds_read_b128 v[202:205], v214 offset:6144
	ds_read_b128 v[216:219], v214 offset:7168
	global_load_lds_dwordx4 v[206:207], off
	s_add_i32 m0, s85, 0xe000
	v_lshl_add_u64 v[206:207], s[8:9], 0, v[184:185]
	global_load_lds_dwordx4 v[206:207], off
	s_waitcnt lgkmcnt(8)
	s_barrier
	s_waitcnt lgkmcnt(0)
	v_mfma_f32_16x16x32_bf16 v[126:129], v[130:133], v[146:149], v[126:129]
	v_mfma_f32_16x16x32_bf16 v[122:125], v[138:141], v[146:149], v[122:125]
	v_mfma_f32_16x16x32_bf16 v[114:117], v[130:133], v[186:189], v[114:117]
	v_mfma_f32_16x16x32_bf16 v[106:109], v[138:141], v[186:189], v[106:109]
	v_mfma_f32_16x16x32_bf16 v[94:97], v[130:133], v[194:197], v[94:97]
	v_mfma_f32_16x16x32_bf16 v[90:93], v[138:141], v[194:197], v[90:93]
	v_mfma_f32_16x16x32_bf16 v[82:85], v[130:133], v[202:205], v[82:85]
	v_mfma_f32_16x16x32_bf16 v[74:77], v[138:141], v[202:205], v[74:77]
	v_mfma_f32_16x16x32_bf16 v[126:129], v[134:137], v[150:153], v[126:129]
	v_mfma_f32_16x16x32_bf16 v[122:125], v[142:145], v[150:153], v[122:125]
	v_mfma_f32_16x16x32_bf16 v[114:117], v[134:137], v[190:193], v[114:117]
	v_mfma_f32_16x16x32_bf16 v[106:109], v[142:145], v[190:193], v[106:109]
	v_mfma_f32_16x16x32_bf16 v[94:97], v[134:137], v[198:201], v[94:97]
	v_mfma_f32_16x16x32_bf16 v[90:93], v[142:145], v[198:201], v[90:93]
	v_mfma_f32_16x16x32_bf16 v[82:85], v[134:137], v[216:219], v[82:85]
	v_mfma_f32_16x16x32_bf16 v[74:77], v[142:145], v[216:219], v[74:77]
	s_barrier
	s_add_i32 s19, 0, 0x14000
	s_add_i32 s26, s27, s84
	v_add_u32_e32 v162, s19, v209
	v_lshl_add_u64 v[206:207], s[46:47], 0, v[8:9]
	s_mov_b32 m0, s26
	ds_read_b128 v[220:223], v162
	ds_read_b128 v[224:227], v162 offset:1024
	ds_read_b128 v[228:231], v162 offset:2048
	ds_read_b128 v[232:235], v162 offset:3072
	global_load_lds_dwordx4 v[206:207], off
	s_add_i32 m0, s26, 0x2000
	v_lshl_add_u64 v[236:237], s[46:47], 0, v[180:181]
	global_load_lds_dwordx4 v[236:237], off
	s_barrier
; #define PG8_STAGE(bufoff, gbase, voff) do { _Pragma("unroll") for (int _i = 0; _i < 2; ++_i) \
;         __builtin_amdgcn_global_load_lds((const unsigned*)((const char*)(gbase) + (voff)[_i]), (LAS unsigned*)(lds + (bufoff) + ldsw + _i * 8192), 16, 0, 0); } while (0)
; #define PG8_LDA(dst, b, h) do { _Pragma("unroll") for (int m = 0; m < 4; ++m) _Pragma("unroll") for (int k = 0; k < 2; ++k) dst[m][k] = *(const LAS bf16x8*)(lds + PG8_SA(b, h) + aoff + m * 2048 + k * 1024); } while (0)
; #define PG8_LDB(dst, b, h) do { _Pragma("unroll") for (int n = 0; n < 2; ++n) _Pragma("unroll") for (int k = 0; k < 2; ++k) dst[n][k] = *(const LAS bf16x8*)(lds + PG8_SB(b, h) + boff + n * 2048 + k * 1024); } while (0)
; #define PG8_MMA(ai, bj, At, Bt) do { __builtin_amdgcn_s_setprio(1); _Pragma("unroll") for (int m = 0; m < 4; ++m) _Pragma("unroll") for (int n = 0; n < 2; ++n) _Pragma("unroll") for (int k = 0; k < 2; ++k) \
;         acc[ai][bj][m][n] = __builtin_amdgcn_mfma_f32_16x16x32_bf16(Bt[n][k], At[m][k], acc[ai][bj][m][n], 0, 0, 0); __builtin_amdgcn_s_setprio(0); } while (0)
; #define PG8_WAIT_V(n) asm volatile("s_waitcnt vmcnt(" #n ")" ::: "memory")
; #define PG8_WAIT_L(n) asm volatile("s_waitcnt lgkmcnt(" #n ")" ::: "memory")
; #define PG8_BAR __builtin_amdgcn_s_barrier()
; #define PG8_SCHED __builtin_amdgcn_sched_barrier(0)
; template <class Epi>
; DEVI void gemm_phase(LAS unsigned char* lds, const Gemm g, const Epi& E) {
;     ...
;             PG8_BAR; PG8_WAIT_L(0); PG8_MMA(0, 1, At, B1); PG8_BAR;
;             PG8_LDA(At, 0, 1); PG8_STAGE(PG8_SA(0, 0), a2, voffA);
;             PG8_BAR; PG8_WAIT_L(0); PG8_MMA(1, 0, At, B0); PG8_BAR; PG8_SCHED;
;             PG8_STAGE(PG8_SB(0, 1), b2 + hstepB, voffB);
;             PG8_WAIT_V(6); PG8_BAR; PG8_MMA(1, 1, At, B1); PG8_BAR;
;             PG8_LDB(B0, 1, 0); PG8_SCHED; PG8_LDA(At, 1, 0); PG8_STAGE(PG8_SA(0, 1), a2 + hstepA, voffA);
;             PG8_WAIT_L(8); PG8_BAR; PG8_WAIT_L(0); PG8_MMA(0, 0, At, B0); PG8_BAR; PG8_SCHED;
;             PG8_LDB(B1, 1, 1); PG8_STAGE(PG8_SB(1, 0), b3, voffB);
;             PG8_BAR; PG8_WAIT_L(0); PG8_MMA(0, 1, At, B1); PG8_BAR;
;             PG8_LDA(At, 1, 1); PG8_STAGE(PG8_SA(1, 0), a3, voffA);
;             PG8_BAR; PG8_WAIT_L(0); PG8_MMA(1, 0, At, B0); PG8_BAR; PG8_SCHED;
	s_waitcnt lgkmcnt(0)
	v_mfma_f32_16x16x32_bf16 v[118:121], v[220:223], v[146:149], v[118:121]
	v_mfma_f32_16x16x32_bf16 v[110:113], v[228:231], v[146:149], v[110:113]
	v_mfma_f32_16x16x32_bf16 v[102:105], v[220:223], v[186:189], v[102:105]
	v_mfma_f32_16x16x32_bf16 v[98:101], v[228:231], v[186:189], v[98:101]
	v_mfma_f32_16x16x32_bf16 v[86:89], v[220:223], v[194:197], v[86:89]
	v_mfma_f32_16x16x32_bf16 v[78:81], v[228:231], v[194:197], v[78:81]
	v_mfma_f32_16x16x32_bf16 v[62:65], v[220:223], v[202:205], v[62:65]
	v_mfma_f32_16x16x32_bf16 v[58:61], v[228:231], v[202:205], v[58:61]
	v_mfma_f32_16x16x32_bf16 v[118:121], v[224:227], v[150:153], v[118:121]
	v_mfma_f32_16x16x32_bf16 v[110:113], v[232:235], v[150:153], v[110:113]
	v_mfma_f32_16x16x32_bf16 v[102:105], v[224:227], v[190:193], v[102:105]
	v_mfma_f32_16x16x32_bf16 v[98:101], v[232:235], v[190:193], v[98:101]
	v_mfma_f32_16x16x32_bf16 v[86:89], v[224:227], v[198:201], v[86:89]
	v_mfma_f32_16x16x32_bf16 v[78:81], v[232:235], v[198:201], v[78:81]
	v_mfma_f32_16x16x32_bf16 v[62:65], v[224:227], v[216:219], v[62:65]
	v_mfma_f32_16x16x32_bf16 v[58:61], v[232:235], v[216:219], v[58:61]
	s_mov_b32 m0, s85
	v_lshl_add_u64 v[238:239], s[68:69], 0, v[176:177]
	s_barrier
	ds_read_b128 v[146:149], v214 offset:16384
	ds_read_b128 v[150:153], v214 offset:17408
	ds_read_b128 v[186:189], v214 offset:18432
	ds_read_b128 v[190:193], v214 offset:19456
	ds_read_b128 v[194:197], v214 offset:20480
	ds_read_b128 v[198:201], v214 offset:21504
	ds_read_b128 v[202:205], v214 offset:22528
	ds_read_b128 v[216:219], v214 offset:23552
	global_load_lds_dwordx4 v[238:239], off
	s_mov_b32 m0, s86
	v_lshl_add_u64 v[240:241], s[68:69], 0, v[178:179]
	global_load_lds_dwordx4 v[240:241], off
	s_barrier
	s_waitcnt lgkmcnt(0)
	v_mfma_f32_16x16x32_bf16 v[70:73], v[130:133], v[146:149], v[70:73]
	v_mfma_f32_16x16x32_bf16 v[66:69], v[138:141], v[146:149], v[66:69]
	v_mfma_f32_16x16x32_bf16 v[46:49], v[130:133], v[186:189], v[46:49]
	v_mfma_f32_16x16x32_bf16 v[42:45], v[138:141], v[186:189], v[42:45]
	v_mfma_f32_16x16x32_bf16 v[30:33], v[130:133], v[194:197], v[30:33]
	v_mfma_f32_16x16x32_bf16 v[26:29], v[138:141], v[194:197], v[26:29]
	v_mfma_f32_16x16x32_bf16 v[14:17], v[130:133], v[202:205], v[14:17]
	v_mfma_f32_16x16x32_bf16 v[10:13], v[138:141], v[202:205], v[10:13]
	v_mfma_f32_16x16x32_bf16 v[70:73], v[134:137], v[150:153], v[70:73]
	v_mfma_f32_16x16x32_bf16 v[66:69], v[142:145], v[150:153], v[66:69]
	v_mfma_f32_16x16x32_bf16 v[46:49], v[134:137], v[190:193], v[46:49]
	v_mfma_f32_16x16x32_bf16 v[42:45], v[142:145], v[190:193], v[42:45]
	v_mfma_f32_16x16x32_bf16 v[30:33], v[134:137], v[198:201], v[30:33]
	v_mfma_f32_16x16x32_bf16 v[26:29], v[142:145], v[198:201], v[26:29]
	v_mfma_f32_16x16x32_bf16 v[14:17], v[134:137], v[216:219], v[14:17]
	v_mfma_f32_16x16x32_bf16 v[10:13], v[142:145], v[216:219], v[10:13]
	s_barrier
	s_add_u32 s26, s46, 0x40000
	s_addc_u32 s27, s47, 0
	s_add_i32 s19, s19, s84
	s_mov_b32 m0, s19
	v_lshl_add_u64 v[130:131], s[26:27], 0, v[8:9]
	global_load_lds_dwordx4 v[130:131], off
	s_add_i32 m0, s19, 0x2000
	v_lshl_add_u64 v[130:131], s[26:27], 0, v[180:181]
	global_load_lds_dwordx4 v[130:131], off
	s_waitcnt vmcnt(6)
	s_barrier
	v_mfma_f32_16x16x32_bf16 v[50:53], v[220:223], v[146:149], v[50:53]
	v_mfma_f32_16x16x32_bf16 v[54:57], v[228:231], v[146:149], v[54:57]
	v_mfma_f32_16x16x32_bf16 v[34:37], v[220:223], v[186:189], v[34:37]
	v_mfma_f32_16x16x32_bf16 v[38:41], v[228:231], v[186:189], v[38:41]
	v_mfma_f32_16x16x32_bf16 v[18:21], v[220:223], v[194:197], v[18:21]
	v_mfma_f32_16x16x32_bf16 v[22:25], v[228:231], v[194:197], v[22:25]
	v_mfma_f32_16x16x32_bf16 v[0:3], v[220:223], v[202:205], v[0:3]
	v_mfma_f32_16x16x32_bf16 v[4:7], v[228:231], v[202:205], v[4:7]
	v_mfma_f32_16x16x32_bf16 v[50:53], v[224:227], v[150:153], v[50:53]
	v_mfma_f32_16x16x32_bf16 v[54:57], v[232:235], v[150:153], v[54:57]
	v_mfma_f32_16x16x32_bf16 v[34:37], v[224:227], v[190:193], v[34:37]
	v_mfma_f32_16x16x32_bf16 v[38:41], v[232:235], v[190:193], v[38:41]
	v_mfma_f32_16x16x32_bf16 v[18:21], v[224:227], v[198:201], v[18:21]
	v_mfma_f32_16x16x32_bf16 v[22:25], v[232:235], v[198:201], v[22:25]
	v_mfma_f32_16x16x32_bf16 v[0:3], v[224:227], v[216:219], v[0:3]
	v_mfma_f32_16x16x32_bf16 v[4:7], v[232:235], v[216:219], v[4:7]
	s_add_i32 s19, 0, 0x18000
	v_add_u32_e32 v142, s19, v209
	s_barrier
	ds_read_b128 v[130:133], v142
	ds_read_b128 v[134:137], v142 offset:1024
	ds_read_b128 v[138:141], v142 offset:2048
	ds_read_b128 v[142:145], v142 offset:3072
	s_add_u32 s26, s68, 0x40000
	s_addc_u32 s27, s69, 0
	s_mov_b32 m0, s87
	v_lshl_add_u64 v[220:221], s[26:27], 0, v[176:177]
	ds_read_b128 v[146:149], v214 offset:32768
	ds_read_b128 v[150:153], v214 offset:33792
	ds_read_b128 v[186:189], v214 offset:34816
	ds_read_b128 v[190:193], v214 offset:35840
	ds_read_b128 v[194:197], v214 offset:36864
	ds_read_b128 v[198:201], v214 offset:37888
	ds_read_b128 v[202:205], v214 offset:38912
	ds_read_b128 v[216:219], v214 offset:39936
	global_load_lds_dwordx4 v[220:221], off
	s_mov_b32 m0, s88
	v_lshl_add_u64 v[220:221], s[26:27], 0, v[178:179]
	global_load_lds_dwordx4 v[220:221], off
	s_waitcnt lgkmcnt(8)
	s_barrier
; #define PG8_STAGE(bufoff, gbase, voff) do { _Pragma("unroll") for (int _i = 0; _i < 2; ++_i) \
;         __builtin_amdgcn_global_load_lds((const unsigned*)((const char*)(gbase) + (voff)[_i]), (LAS unsigned*)(lds + (bufoff) + ldsw + _i * 8192), 16, 0, 0); } while (0)
; #define PG8_LDA(dst, b, h) do { _Pragma("unroll") for (int m = 0; m < 4; ++m) _Pragma("unroll") for (int k = 0; k < 2; ++k) dst[m][k] = *(const LAS bf16x8*)(lds + PG8_SA(b, h) + aoff + m * 2048 + k * 1024); } while (0)
; #define PG8_LDB(dst, b, h) do { _Pragma("unroll") for (int n = 0; n < 2; ++n) _Pragma("unroll") for (int k = 0; k < 2; ++k) dst[n][k] = *(const LAS bf16x8*)(lds + PG8_SB(b, h) + boff + n * 2048 + k * 1024); } while (0)
; #define PG8_MMA(ai, bj, At, Bt) do { __builtin_amdgcn_s_setprio(1); _Pragma("unroll") for (int m = 0; m < 4; ++m) _Pragma("unroll") for (int n = 0; n < 2; ++n) _Pragma("unroll") for (int k = 0; k < 2; ++k) \
;         acc[ai][bj][m][n] = __builtin_amdgcn_mfma_f32_16x16x32_bf16(Bt[n][k], At[m][k], acc[ai][bj][m][n], 0, 0, 0); __builtin_amdgcn_s_setprio(0); } while (0)
; #define PG8_WAIT_V(n) asm volatile("s_waitcnt vmcnt(" #n ")" ::: "memory")
; #define PG8_WAIT_L(n) asm volatile("s_waitcnt lgkmcnt(" #n ")" ::: "memory")
; #define PG8_BAR __builtin_amdgcn_s_barrier()
; #define PG8_SCHED __builtin_amdgcn_sched_barrier(0)
; template <class Epi>
; DEVI void gemm_phase(LAS unsigned char* lds, const Gemm g, const Epi& E) {
;     ...
;             PG8_BAR; PG8_WAIT_L(0); PG8_MMA(1, 0, At, B0); PG8_BAR; PG8_SCHED;
;             PG8_STAGE(PG8_SB(0, 1), b2 + hstepB, voffB);
;             PG8_WAIT_V(6); PG8_BAR; PG8_MMA(1, 1, At, B1); PG8_BAR;
;             PG8_LDB(B0, 1, 0); PG8_SCHED; PG8_LDA(At, 1, 0); PG8_STAGE(PG8_SA(0, 1), a2 + hstepA, voffA);
;             PG8_WAIT_L(8); PG8_BAR; PG8_WAIT_L(0); PG8_MMA(0, 0, At, B0); PG8_BAR; PG8_SCHED;
;             PG8_LDB(B1, 1, 1); PG8_STAGE(PG8_SB(1, 0), b3, voffB);
;             PG8_BAR; PG8_WAIT_L(0); PG8_MMA(0, 1, At, B1); PG8_BAR;
;             PG8_LDA(At, 1, 1); PG8_STAGE(PG8_SA(1, 0), a3, voffA);
;             PG8_BAR; PG8_WAIT_L(0); PG8_MMA(1, 0, At, B0); PG8_BAR; PG8_SCHED;
;             PG8_STAGE(PG8_SB(1, 1), b3 + hstepB, voffB);
;             PG8_WAIT_V(6); PG8_BAR; PG8_MMA(1, 1, At, B1); PG8_BAR;
;         }
	s_waitcnt lgkmcnt(0)
	v_mfma_f32_16x16x32_bf16 v[126:129], v[130:133], v[146:149], v[126:129]
	v_mfma_f32_16x16x32_bf16 v[122:125], v[138:141], v[146:149], v[122:125]
	v_mfma_f32_16x16x32_bf16 v[114:117], v[130:133], v[186:189], v[114:117]
	v_mfma_f32_16x16x32_bf16 v[106:109], v[138:141], v[186:189], v[106:109]
	v_mfma_f32_16x16x32_bf16 v[94:97], v[130:133], v[194:197], v[94:97]
	v_mfma_f32_16x16x32_bf16 v[90:93], v[138:141], v[194:197], v[90:93]
	v_mfma_f32_16x16x32_bf16 v[82:85], v[130:133], v[202:205], v[82:85]
	v_mfma_f32_16x16x32_bf16 v[74:77], v[138:141], v[202:205], v[74:77]
	v_mfma_f32_16x16x32_bf16 v[126:129], v[134:137], v[150:153], v[126:129]
	v_mfma_f32_16x16x32_bf16 v[122:125], v[142:145], v[150:153], v[122:125]
	v_mfma_f32_16x16x32_bf16 v[114:117], v[134:137], v[190:193], v[114:117]
	v_mfma_f32_16x16x32_bf16 v[106:109], v[142:145], v[190:193], v[106:109]
	v_mfma_f32_16x16x32_bf16 v[94:97], v[134:137], v[198:201], v[94:97]
	v_mfma_f32_16x16x32_bf16 v[90:93], v[142:145], v[198:201], v[90:93]
	v_mfma_f32_16x16x32_bf16 v[82:85], v[134:137], v[216:219], v[82:85]
	v_mfma_f32_16x16x32_bf16 v[74:77], v[142:145], v[216:219], v[74:77]
	s_barrier
	s_add_i32 s38, 0, 0x1c000
	s_add_i32 s19, s19, s84
	v_add_u32_e32 v162, s38, v209
	v_lshl_add_u64 v[206:207], v[206:207], 0, s[70:71]
	s_mov_b32 m0, s19
	ds_read_b128 v[220:223], v162
	ds_read_b128 v[224:227], v162 offset:1024
	ds_read_b128 v[228:231], v162 offset:2048
	ds_read_b128 v[232:235], v162 offset:3072
	global_load_lds_dwordx4 v[206:207], off
	s_add_i32 m0, s19, 0x2000
	v_lshl_add_u64 v[206:207], v[236:237], 0, s[70:71]
	global_load_lds_dwordx4 v[206:207], off
	s_barrier
	s_waitcnt lgkmcnt(0)
	v_mfma_f32_16x16x32_bf16 v[118:121], v[220:223], v[146:149], v[118:121]
	v_mfma_f32_16x16x32_bf16 v[110:113], v[228:231], v[146:149], v[110:113]
	v_mfma_f32_16x16x32_bf16 v[102:105], v[220:223], v[186:189], v[102:105]
	v_mfma_f32_16x16x32_bf16 v[98:101], v[228:231], v[186:189], v[98:101]
	v_mfma_f32_16x16x32_bf16 v[86:89], v[220:223], v[194:197], v[86:89]
	v_mfma_f32_16x16x32_bf16 v[78:81], v[228:231], v[194:197], v[78:81]
	v_mfma_f32_16x16x32_bf16 v[62:65], v[220:223], v[202:205], v[62:65]
	v_mfma_f32_16x16x32_bf16 v[58:61], v[228:231], v[202:205], v[58:61]
	v_mfma_f32_16x16x32_bf16 v[118:121], v[224:227], v[150:153], v[118:121]
	v_mfma_f32_16x16x32_bf16 v[110:113], v[232:235], v[150:153], v[110:113]
	v_mfma_f32_16x16x32_bf16 v[102:105], v[224:227], v[190:193], v[102:105]
	v_mfma_f32_16x16x32_bf16 v[98:101], v[232:235], v[190:193], v[98:101]
	v_mfma_f32_16x16x32_bf16 v[86:89], v[224:227], v[198:201], v[86:89]
	v_mfma_f32_16x16x32_bf16 v[78:81], v[232:235], v[198:201], v[78:81]
	v_mfma_f32_16x16x32_bf16 v[62:65], v[224:227], v[216:219], v[62:65]
	v_mfma_f32_16x16x32_bf16 v[58:61], v[232:235], v[216:219], v[58:61]
	s_mov_b32 m0, s89
	v_lshl_add_u64 v[206:207], v[238:239], 0, s[70:71]
	s_barrier
	ds_read_b128 v[146:149], v214 offset:49152
	ds_read_b128 v[150:153], v214 offset:50176
	ds_read_b128 v[186:189], v214 offset:51200
	ds_read_b128 v[190:193], v214 offset:52224
	ds_read_b128 v[194:197], v214 offset:53248
	ds_read_b128 v[198:201], v214 offset:54272
	ds_read_b128 v[202:205], v214 offset:55296
	ds_read_b128 v[216:219], v214 offset:56320
	global_load_lds_dwordx4 v[206:207], off
	s_mov_b32 m0, s90
	v_lshl_add_u64 v[206:207], v[240:241], 0, s[70:71]
	global_load_lds_dwordx4 v[206:207], off
	s_barrier
	s_waitcnt lgkmcnt(0)
	v_mfma_f32_16x16x32_bf16 v[70:73], v[130:133], v[146:149], v[70:73]
	v_mfma_f32_16x16x32_bf16 v[66:69], v[138:141], v[146:149], v[66:69]
	v_mfma_f32_16x16x32_bf16 v[46:49], v[130:133], v[186:189], v[46:49]
	v_mfma_f32_16x16x32_bf16 v[42:45], v[138:141], v[186:189], v[42:45]
	v_mfma_f32_16x16x32_bf16 v[30:33], v[130:133], v[194:197], v[30:33]
	v_mfma_f32_16x16x32_bf16 v[26:29], v[138:141], v[194:197], v[26:29]
	v_mfma_f32_16x16x32_bf16 v[14:17], v[130:133], v[202:205], v[14:17]
	v_mfma_f32_16x16x32_bf16 v[10:13], v[138:141], v[202:205], v[10:13]
	v_mfma_f32_16x16x32_bf16 v[70:73], v[134:137], v[150:153], v[70:73]
	v_mfma_f32_16x16x32_bf16 v[66:69], v[142:145], v[150:153], v[66:69]
	v_mfma_f32_16x16x32_bf16 v[46:49], v[134:137], v[190:193], v[46:49]
	v_mfma_f32_16x16x32_bf16 v[42:45], v[142:145], v[190:193], v[42:45]
	v_mfma_f32_16x16x32_bf16 v[30:33], v[134:137], v[198:201], v[30:33]
	v_mfma_f32_16x16x32_bf16 v[26:29], v[142:145], v[198:201], v[26:29]
	v_mfma_f32_16x16x32_bf16 v[14:17], v[134:137], v[216:219], v[14:17]
	v_mfma_f32_16x16x32_bf16 v[10:13], v[142:145], v[216:219], v[10:13]
	s_barrier
	s_add_u32 s26, s46, 0x40080
	s_addc_u32 s27, s47, 0
	s_add_i32 s19, s38, s84
	s_mov_b32 m0, s19
	v_lshl_add_u64 v[130:131], s[26:27], 0, v[8:9]
	global_load_lds_dwordx4 v[130:131], off
	s_add_i32 m0, s19, 0x2000
	v_lshl_add_u64 v[130:131], s[26:27], 0, v[180:181]
	global_load_lds_dwordx4 v[130:131], off
	s_waitcnt vmcnt(6)
	s_barrier
	v_mfma_f32_16x16x32_bf16 v[50:53], v[220:223], v[146:149], v[50:53]
	v_mfma_f32_16x16x32_bf16 v[54:57], v[228:231], v[146:149], v[54:57]
	v_mfma_f32_16x16x32_bf16 v[34:37], v[220:223], v[186:189], v[34:37]
	v_mfma_f32_16x16x32_bf16 v[38:41], v[228:231], v[186:189], v[38:41]
	v_mfma_f32_16x16x32_bf16 v[18:21], v[220:223], v[194:197], v[18:21]
	v_mfma_f32_16x16x32_bf16 v[22:25], v[228:231], v[194:197], v[22:25]
	v_mfma_f32_16x16x32_bf16 v[0:3], v[220:223], v[202:205], v[0:3]
	v_mfma_f32_16x16x32_bf16 v[4:7], v[228:231], v[202:205], v[4:7]
	v_mfma_f32_16x16x32_bf16 v[50:53], v[224:227], v[150:153], v[50:53]
	v_mfma_f32_16x16x32_bf16 v[54:57], v[232:235], v[150:153], v[54:57]
	v_mfma_f32_16x16x32_bf16 v[34:37], v[224:227], v[190:193], v[34:37]
	v_mfma_f32_16x16x32_bf16 v[38:41], v[232:235], v[190:193], v[38:41]
	v_mfma_f32_16x16x32_bf16 v[18:21], v[224:227], v[198:201], v[18:21]
	v_mfma_f32_16x16x32_bf16 v[22:25], v[232:235], v[198:201], v[22:25]
	v_mfma_f32_16x16x32_bf16 v[0:3], v[224:227], v[216:219], v[0:3]
	v_mfma_f32_16x16x32_bf16 v[4:7], v[232:235], v[216:219], v[4:7]
	s_add_i32 s18, s18, 2
	s_add_u32 s8, s8, 0x100
	s_addc_u32 s9, s9, 0
	s_add_u32 s11, s11, 0x100
	s_addc_u32 s13, s13, 0
	s_cmp_gt_u32 s18, 13
	s_barrier
	s_cbranch_scc0 .LBB0_356
	s_branch .Lip13l_b_out
; DEVI size_t gemm_offB(const Gemm& g, const Unit& u) { return (g.split ? (size_t)(u.b >> 2) * g.sB + (size_t)(u.b & 3) * g.sB_lo : (size_t)u.b * g.sB) + (size_t)(u.pm >> g.pmsh) * g.sBpm; }
; #define PG8_STAGE(bufoff, gbase, voff) do { _Pragma("unroll") for (int _i = 0; _i < 2; ++_i) \
;         __builtin_amdgcn_global_load_lds((const unsigned*)((const char*)(gbase) + (voff)[_i]), (LAS unsigned*)(lds + (bufoff) + ldsw + _i * 8192), 16, 0, 0); } while (0)
; #define PG8_LDA(dst, b, h) do { _Pragma("unroll") for (int m = 0; m < 4; ++m) _Pragma("unroll") for (int k = 0; k < 2; ++k) dst[m][k] = *(const LAS bf16x8*)(lds + PG8_SA(b, h) + aoff + m * 2048 + k * 1024); } while (0)
; #define PG8_LDB(dst, b, h) do { _Pragma("unroll") for (int n = 0; n < 2; ++n) _Pragma("unroll") for (int k = 0; k < 2; ++k) dst[n][k] = *(const LAS bf16x8*)(lds + PG8_SB(b, h) + boff + n * 2048 + k * 1024); } while (0)
; #define PG8_MMA(ai, bj, At, Bt) do { __builtin_amdgcn_s_setprio(1); _Pragma("unroll") for (int m = 0; m < 4; ++m) _Pragma("unroll") for (int n = 0; n < 2; ++n) _Pragma("unroll") for (int k = 0; k < 2; ++k) \
;         acc[ai][bj][m][n] = __builtin_amdgcn_mfma_f32_16x16x32_bf16(Bt[n][k], At[m][k], acc[ai][bj][m][n], 0, 0, 0); __builtin_amdgcn_s_setprio(0); } while (0)
; #define PG8_WAIT_L(n) asm volatile("s_waitcnt lgkmcnt(" #n ")" ::: "memory")
; #define PG8_BAR __builtin_amdgcn_s_barrier()
; #define PG8_SCHED __builtin_amdgcn_sched_barrier(0)
; template <class Epi>
; DEVI void gemm_phase(LAS unsigned char* lds, const Gemm g, const Epi& E) {
;     ...
;         const bool has_next = unit_next(g, ui + 1, nxt);
;         const char* nA = has_next ? (const char*)g.A + gemm_offA(g, nxt) * 2 + (size_t)nxt.pm * tstepA : cA;
;         const char* nB = has_next ? (const char*)g.Bt + gemm_offB(g, nxt) * 2 + (size_t)nxt.pn * tstepB : cB;
;         for (int t = 0; t < nt; t += 2) {
;             const bool last = (t == nt - 2);
;             const char* a1 = cA + (size_t)(t + 1) * kstep;
;             const char* a2 = last ? nA : cA + (size_t)(t + 2) * kstep; const char* b2 = last ? nB : cB + (size_t)(t + 2) * kstep;
;             const char* a3 = a2 + kstep; const char* b3 = b2 + kstep;
;             PG8_LDB(B0, 0, 0); PG8_SCHED; PG8_LDA(At, 0, 0); PG8_STAGE(PG8_SA(1, 1), a1 + hstepA, voffA);
;             PG8_WAIT_L(8); PG8_BAR; PG8_WAIT_L(0); PG8_MMA(0, 0, At, B0); PG8_BAR; PG8_SCHED;
.Lip13l_b_in:
	s_and_b32 s101, s66, 0xc0
	s_mov_b32 s100, 1
	s_cmp_lg_u32 s101, 0
	s_cselect_b32 s101, 1, 0
	s_add_u32 s19, s8, 0xfffc0080
	s_addc_u32 s26, s9, -1
	s_add_i32 s27, 0, 0x10000
	v_add_u32_e32 v142, s27, v209
	ds_read_b128 v[130:133], v142
	ds_read_b128 v[134:137], v142 offset:1024
	ds_read_b128 v[138:141], v142 offset:2048
	ds_read_b128 v[142:145], v142 offset:3072
	s_cmp_eq_u32 s18, 12
	s_cselect_b32 s69, s0, s26
	s_cselect_b32 s68, s1, s19
	s_cselect_b32 s47, s5, s13
	s_cselect_b32 s46, s7, s11
	v_lshl_add_u64 v[206:207], s[8:9], 0, v[182:183]
	s_add_i32 m0, s85, 0xc000
	ds_read_b128 v[146:149], v214
	ds_read_b128 v[150:153], v214 offset:1024
	ds_read_b128 v[186:189], v214 offset:2048
	ds_read_b128 v[190:193], v214 offset:3072
	ds_read_b128 v[194:197], v214 offset:4096
	ds_read_b128 v[198:201], v214 offset:5120
	ds_read_b128 v[202:205], v214 offset:6144
	ds_read_b128 v[216:219], v214 offset:7168
	global_load_lds_dwordx4 v[206:207], off
	s_add_i32 m0, s85, 0xe000
	v_lshl_add_u64 v[206:207], s[8:9], 0, v[184:185]
	global_load_lds_dwordx4 v[206:207], off
	s_waitcnt lgkmcnt(8)
	s_barrier
	s_waitcnt lgkmcnt(0)
	s_cmp_lg_u32 s101, 0
	s_cbranch_scc1 .Lip13l_b_0
	v_mfma_f32_16x16x32_bf16 v[126:129], v[130:133], v[146:149], 0
	v_mfma_f32_16x16x32_bf16 v[122:125], v[138:141], v[146:149], 0
	v_mfma_f32_16x16x32_bf16 v[114:117], v[130:133], v[186:189], 0
	v_mfma_f32_16x16x32_bf16 v[106:109], v[138:141], v[186:189], 0
	v_mfma_f32_16x16x32_bf16 v[94:97], v[130:133], v[194:197], 0
	v_mfma_f32_16x16x32_bf16 v[90:93], v[138:141], v[194:197], 0
	v_mfma_f32_16x16x32_bf16 v[82:85], v[130:133], v[202:205], 0
	v_mfma_f32_16x16x32_bf16 v[74:77], v[138:141], v[202:205], 0
	v_mfma_f32_16x16x32_bf16 v[126:129], v[134:137], v[150:153], v[126:129]
	v_mfma_f32_16x16x32_bf16 v[122:125], v[142:145], v[150:153], v[122:125]
	v_mfma_f32_16x16x32_bf16 v[114:117], v[134:137], v[190:193], v[114:117]
	v_mfma_f32_16x16x32_bf16 v[106:109], v[142:145], v[190:193], v[106:109]
	v_mfma_f32_16x16x32_bf16 v[94:97], v[134:137], v[198:201], v[94:97]
	v_mfma_f32_16x16x32_bf16 v[90:93], v[142:145], v[198:201], v[90:93]
	v_mfma_f32_16x16x32_bf16 v[82:85], v[134:137], v[216:219], v[82:85]
	v_mfma_f32_16x16x32_bf16 v[74:77], v[142:145], v[216:219], v[74:77]

; template <class Epi>
; DEVI void gemm_phase(LAS unsigned char* lds, const Gemm g, const Epi& E) {
;     ...
;             const int row0 = cur.pm * BM + wr * 64 + fr, col0 = cur.pn * BM + wc * 32 + (Epi::PERM ? 8 : 4) * fq; constexpr int NST = Epi::PERM ? 4 : 16;
;             float rsv[8];
;             if constexpr (Epi::RS) { f32x4 q4[8];
; #pragma unroll
;                 for (int i = 0; i < 8; ++i) q4[i] = *(const f32x4*)(E.ssq_in + (size_t)(row0 + (i >> 2) * HALF + (i & 3) * 16) * 4);
; #pragma unroll
;                 for (int i = 0; i < 8; ++i) rsv[i] = rsqrtf((((q4[i][0] + q4[i][1]) + q4[i][2]) + q4[i][3]) * (1.f / DM) + 1e-6f); }
.Lip13l_b_out:
	s_setprio 0
	v_lshl_add_u32 v202, s6, 8, v208
	v_ashrrev_i32_e32 v203, 31, v202
	v_or_b32_e32 v200, 16, v202
	v_lshl_add_u64 v[130:131], v[202:203], 4, s[76:77]
	v_ashrrev_i32_e32 v201, 31, v200
	v_lshl_add_u64 v[132:133], v[200:201], 4, s[76:77]
	global_load_dwordx4 v[204:207], v[130:131], off
	global_load_dwordx4 v[216:219], v[132:133], off
	v_or_b32_e32 v198, 32, v202
	v_ashrrev_i32_e32 v199, 31, v198
	v_or_b32_e32 v196, 48, v202
	v_add_u32_e32 v194, 0x80, v202
	v_lshl_add_u64 v[130:131], v[198:199], 4, s[76:77]
	v_ashrrev_i32_e32 v197, 31, v196
	v_ashrrev_i32_e32 v195, 31, v194
	v_add_u32_e32 v192, 0x90, v202
	v_add_u32_e32 v190, 0xa0, v202
	v_add_u32_e32 v188, 0xb0, v202
	v_lshl_add_u64 v[132:133], v[196:197], 4, s[76:77]
	global_load_dwordx4 v[146:149], v[130:131], off
	global_load_dwordx4 v[150:153], v[132:133], off
	v_lshl_add_u64 v[130:131], v[194:195], 4, s[76:77]
	v_ashrrev_i32_e32 v193, 31, v192
	v_ashrrev_i32_e32 v191, 31, v190
	v_ashrrev_i32_e32 v189, 31, v188
	v_lshl_add_u64 v[132:133], v[192:193], 4, s[76:77]
	global_load_dwordx4 v[138:141], v[130:131], off
	global_load_dwordx4 v[142:145], v[132:133], off
	v_lshl_add_u64 v[130:131], v[190:191], 4, s[76:77]
	v_lshl_add_u64 v[134:135], v[188:189], 4, s[76:77]
	global_load_dwordx4 v[130:133], v[130:131], off
	s_nop 0
	global_load_dwordx4 v[134:137], v[134:135], off
	s_waitcnt vmcnt(0)
	v_mov_b32_e32 v187, v204
	v_mov_b32_e32 v186, v216
	v_mov_b32_e32 v204, v217
	v_mov_b32_e32 v221, v206
	v_mov_b32_e32 v220, v218
	v_pk_add_f32 v[186:187], v[186:187], v[204:205]
	v_mov_b32_e32 v206, v219
	v_pk_add_f32 v[186:187], v[220:221], v[186:187]
	s_nop 0
	v_pk_add_f32 v[186:187], v[206:207], v[186:187]
	s_nop 0
	v_pk_fma_f32 v[204:205], v[186:187], s[72:73], v[160:161] op_sel_hi:[1,0,0]
	v_lshl_or_b32 v186, s4, 8, v213
	v_mul_f32_e32 v162, 0x4b800000, v205
	v_cmp_gt_f32_e32 vcc, s94, v205
	v_cmp_gt_f32_e64 s[6:7], s94, v204
	s_nop 0
	v_cndmask_b32_e32 v162, v205, v162, vcc
	v_rsq_f32_e32 v162, v162
	s_nop 0
	v_mul_f32_e32 v163, 0x45800000, v162
	v_cndmask_b32_e32 v206, v162, v163, vcc
	v_pk_mul_f32 v[128:129], v[128:129], v[206:207] op_sel_hi:[1,0]
	v_pk_mul_f32 v[126:127], v[126:127], v[206:207] op_sel_hi:[1,0]
	v_pk_mul_f32 v[124:125], v[124:125], v[206:207] op_sel_hi:[1,0]
	v_pk_mul_f32 v[122:123], v[122:123], v[206:207] op_sel_hi:[1,0]
	v_cmp_lt_i32_e32 vcc, s52, v186
	s_and_saveexec_b64 s[0:1], vcc
	s_xor_b64 s[8:9], exec, s[0:1]
	s_cbranch_execz .LBB0_361
	v_cmp_eq_u32_e64 s[4:5], s53, v186
	s_and_saveexec_b64 s[46:47], s[4:5]
	s_cbranch_execz .LBB0_360
	v_lshlrev_b64 v[216:217], 6, v[202:203]
	v_lshl_add_u64 v[216:217], s[58:59], 0, v[216:217]
	global_store_dwordx4 v[216:217], v[126:129], off
	global_store_dwordx4 v[216:217], v[122:125], off offset:16
